# v10: v4 + MFMA order inside each 16-group: the two k-steps of an accumulator back to back
# speedup vs baseline: 1.0132x; 1.0068x over previous
; #define PG8_STAGE(bufoff, gbase, voff) do { _Pragma("unroll") for (int _i = 0; _i < 2; ++_i) \
;         __builtin_amdgcn_global_load_lds((const unsigned*)((const char*)(gbase) + (voff)[_i]), (PG8_LAS unsigned*)(lds + (bufoff) + ldsw + _i * 8192), 16, 0, 0); } while (0)
; #define PG8_LDA(dst, b, h) do { _Pragma("unroll") for (int m = 0; m < 4; ++m) _Pragma("unroll") for (int k = 0; k < 2; ++k) dst[m][k] = *(const PG8_LAS bf16x8*)(lds + PG8_SA(b, h) + aoff + m * 2048 + k * 1024); } while (0)
; #define PG8_LDB(dst, b, h) do { _Pragma("unroll") for (int n = 0; n < 2; ++n) _Pragma("unroll") for (int k = 0; k < 2; ++k) dst[n][k] = *(const PG8_LAS bf16x8*)(lds + PG8_SB(b, h) + boff + n * 2048 + k * 1024); } while (0)
; #define PG8_MMA(ai, bj, At, Bt) do { __builtin_amdgcn_s_setprio(1); _Pragma("unroll") for (int m = 0; m < 4; ++m) _Pragma("unroll") for (int n = 0; n < 2; ++n) _Pragma("unroll") for (int k = 0; k < 2; ++k) \
;         acc[ai][bj][m][n] = __builtin_amdgcn_mfma_f32_16x16x32_bf16(Bt[n][k], At[m][k], acc[ai][bj][m][n], 0, 0, 0); __builtin_amdgcn_s_setprio(0); } while (0)
; #define PG8_WAIT_V(n) asm volatile("s_waitcnt vmcnt(" #n ")" ::: "memory")
; #define PG8_WAIT_L(n) asm volatile("s_waitcnt lgkmcnt(" #n ")" ::: "memory")
; #define PG8_BAR __builtin_amdgcn_s_barrier()
; #define PG8_SCHED __builtin_amdgcn_sched_barrier(0)
; template <class Epi, class Sched, bool ALIGN_EPI = false, bool SP2 = false>
; __device__ __forceinline__ void gemm_phase(PG8_LAS unsigned char* lds, const Gemm g, const Sched& S, const Epi& E) {
;     ...
;             PG8_LDB(B0, 0, 0); PG8_LDB(B1, 0, 1); PG8_SCHED; PG8_LDA(At, 0, 0); PG8_STAGE(PG8_SA(1, 1), a1 + hstep, voffA);
;             PG8_WAIT_V(8); PG8_WAIT_L(0); PG8_BAR; PG8_MMA(0, 0, At, B0); PG8_MMA(0, 1, At, B1); PG8_BAR; PG8_SCHED;
;             PG8_LDA(At, 0, 1); PG8_STAGE(PG8_SB(0, 0), b2, voffB); PG8_STAGE(PG8_SB(0, 1), b2 + hstep, voffB); PG8_STAGE(PG8_SA(0, 0), a2, voffA);
;             PG8_WAIT_V(8); PG8_WAIT_L(0); PG8_BAR; PG8_MMA(1, 0, At, B0); PG8_MMA(1, 1, At, B1); PG8_BAR; PG8_SCHED;
.LBB0_115:
	ds_read_b128 v[154:157], v150
	ds_read_b128 v[158:161], v150 offset:1024
	ds_read_b128 v[162:165], v150 offset:2048
	ds_read_b128 v[166:169], v150 offset:3072
	ds_read_b128 v[170:173], v151
	ds_read_b128 v[174:177], v151 offset:1024
	ds_read_b128 v[180:183], v151 offset:2048
	ds_read_b128 v[184:187], v151 offset:3072
	s_add_u32 s50, s48, 0x4000
	s_addc_u32 s51, s49, 0
	s_cmp_eq_u32 s76, 60
	s_cselect_b32 s74, s64, s50
	s_cselect_b32 s75, s25, s51
	s_cselect_b32 s72, s65, s68
	s_cselect_b32 s73, s19, s69
	s_add_u32 s50, s74, 0x8000
	s_addc_u32 s51, s75, 0
	s_sub_u32 s50, s48, 0x4000
	s_subb_u32 s51, s49, 0
	v_lshl_add_u64 v[224:225], s[50:51], 0, v[130:131]
	s_mov_b32 m0, s58
	s_nop 0
	global_load_lds_dwordx4 v[224:225], off
	v_lshl_add_u64 v[224:225], s[50:51], 0, v[134:135]
	s_mov_b32 m0, s59
	s_nop 0
	global_load_lds_dwordx4 v[224:225], off
	v_lshl_add_u64 v[224:225], s[48:49], 0, v[140:141]
	s_add_i32 m0, s28, 0xc000
	ds_read_b128 v[188:191], v152
	ds_read_b128 v[196:199], v152 offset:1024
	ds_read_b128 v[200:203], v152 offset:2048
	ds_read_b128 v[204:207], v152 offset:3072
	ds_read_b128 v[208:211], v152 offset:4096
	ds_read_b128 v[212:215], v152 offset:5120
	ds_read_b128 v[216:219], v152 offset:6144
	ds_read_b128 v[220:223], v152 offset:7168
	global_load_lds_dwordx4 v[224:225], off
	v_lshl_add_u64 v[224:225], s[48:49], 0, v[142:143]
	s_add_i32 m0, s28, 0xe000
	s_nop 0
	global_load_lds_dwordx4 v[224:225], off
	s_waitcnt vmcnt(8)
	s_waitcnt lgkmcnt(0)
	s_barrier
	s_setprio 1
	s_waitcnt lgkmcnt(0)
	v_mfma_f32_16x16x32_bf16 v[126:129], v[154:157], v[188:191], v[126:129]
	v_mfma_f32_16x16x32_bf16 v[126:129], v[158:161], v[196:199], v[126:129]
	v_mfma_f32_16x16x32_bf16 v[118:121], v[162:165], v[188:191], v[118:121]
	v_mfma_f32_16x16x32_bf16 v[118:121], v[166:169], v[196:199], v[118:121]
	v_mfma_f32_16x16x32_bf16 v[110:113], v[154:157], v[200:203], v[110:113]
	v_mfma_f32_16x16x32_bf16 v[110:113], v[158:161], v[204:207], v[110:113]
	v_mfma_f32_16x16x32_bf16 v[102:105], v[162:165], v[200:203], v[102:105]
	v_mfma_f32_16x16x32_bf16 v[102:105], v[166:169], v[204:207], v[102:105]
	v_mfma_f32_16x16x32_bf16 v[94:97], v[154:157], v[208:211], v[94:97]
	v_mfma_f32_16x16x32_bf16 v[94:97], v[158:161], v[212:215], v[94:97]
	v_mfma_f32_16x16x32_bf16 v[86:89], v[162:165], v[208:211], v[86:89]
	v_mfma_f32_16x16x32_bf16 v[86:89], v[166:169], v[212:215], v[86:89]
	v_mfma_f32_16x16x32_bf16 v[78:81], v[154:157], v[216:219], v[78:81]
	v_mfma_f32_16x16x32_bf16 v[78:81], v[158:161], v[220:223], v[78:81]
	v_mfma_f32_16x16x32_bf16 v[70:73], v[162:165], v[216:219], v[70:73]
	v_mfma_f32_16x16x32_bf16 v[70:73], v[166:169], v[220:223], v[70:73]
	s_setprio 0
	s_setprio 1
	v_mfma_f32_16x16x32_bf16 v[122:125], v[170:173], v[188:191], v[122:125]
	v_mfma_f32_16x16x32_bf16 v[122:125], v[174:177], v[196:199], v[122:125]
	v_mfma_f32_16x16x32_bf16 v[114:117], v[180:183], v[188:191], v[114:117]
	v_mfma_f32_16x16x32_bf16 v[114:117], v[184:187], v[196:199], v[114:117]
	v_mfma_f32_16x16x32_bf16 v[106:109], v[170:173], v[200:203], v[106:109]
	v_mfma_f32_16x16x32_bf16 v[106:109], v[174:177], v[204:207], v[106:109]
	v_mfma_f32_16x16x32_bf16 v[98:101], v[180:183], v[200:203], v[98:101]
	v_mfma_f32_16x16x32_bf16 v[98:101], v[184:187], v[204:207], v[98:101]
	v_mfma_f32_16x16x32_bf16 v[90:93], v[170:173], v[208:211], v[90:93]
	v_mfma_f32_16x16x32_bf16 v[90:93], v[174:177], v[212:215], v[90:93]
	v_mfma_f32_16x16x32_bf16 v[82:85], v[180:183], v[208:211], v[82:85]
	v_mfma_f32_16x16x32_bf16 v[82:85], v[184:187], v[212:215], v[82:85]
	v_mfma_f32_16x16x32_bf16 v[74:77], v[170:173], v[216:219], v[74:77]
	v_mfma_f32_16x16x32_bf16 v[74:77], v[174:177], v[220:223], v[74:77]
	v_mfma_f32_16x16x32_bf16 v[66:69], v[180:183], v[216:219], v[66:69]
	v_mfma_f32_16x16x32_bf16 v[66:69], v[184:187], v[220:223], v[66:69]
	s_setprio 0
	s_barrier
	s_add_i32 s77, s61, s3
	v_lshl_add_u64 v[224:225], s[72:73], 0, v[132:133]
	s_mov_b32 m0, s77
	ds_read_b128 v[188:191], v152 offset:16384
	ds_read_b128 v[196:199], v152 offset:17408
	ds_read_b128 v[200:203], v152 offset:18432
	ds_read_b128 v[204:207], v152 offset:19456
	ds_read_b128 v[208:211], v152 offset:20480
	ds_read_b128 v[212:215], v152 offset:21504
	ds_read_b128 v[216:219], v152 offset:22528
	ds_read_b128 v[220:223], v152 offset:23552
	global_load_lds_dwordx4 v[224:225], off
	s_add_i32 m0, s77, 0x2000
	s_add_u32 s78, s72, 0x4000
	v_lshl_add_u64 v[224:225], s[72:73], 0, v[136:137]
	s_addc_u32 s79, s73, 0
	s_add_i32 s77, s62, s3
	global_load_lds_dwordx4 v[224:225], off
	v_lshl_add_u64 v[224:225], s[78:79], 0, v[132:133]
	s_mov_b32 m0, s77
	s_nop 0
	global_load_lds_dwordx4 v[224:225], off
	v_lshl_add_u64 v[224:225], s[78:79], 0, v[136:137]
	s_add_i32 m0, s77, 0x2000
	s_nop 0
	global_load_lds_dwordx4 v[224:225], off
	s_waitcnt vmcnt(6)
	s_waitcnt lgkmcnt(0)
	s_barrier
; #define PG8_STAGE(bufoff, gbase, voff) do { _Pragma("unroll") for (int _i = 0; _i < 2; ++_i) \
;         __builtin_amdgcn_global_load_lds((const unsigned*)((const char*)(gbase) + (voff)[_i]), (PG8_LAS unsigned*)(lds + (bufoff) + ldsw + _i * 8192), 16, 0, 0); } while (0)
; #define PG8_LDA(dst, b, h) do { _Pragma("unroll") for (int m = 0; m < 4; ++m) _Pragma("unroll") for (int k = 0; k < 2; ++k) dst[m][k] = *(const PG8_LAS bf16x8*)(lds + PG8_SA(b, h) + aoff + m * 2048 + k * 1024); } while (0)
; #define PG8_LDB(dst, b, h) do { _Pragma("unroll") for (int n = 0; n < 2; ++n) _Pragma("unroll") for (int k = 0; k < 2; ++k) dst[n][k] = *(const PG8_LAS bf16x8*)(lds + PG8_SB(b, h) + boff + n * 2048 + k * 1024); } while (0)
; #define PG8_MMA(ai, bj, At, Bt) do { __builtin_amdgcn_s_setprio(1); _Pragma("unroll") for (int m = 0; m < 4; ++m) _Pragma("unroll") for (int n = 0; n < 2; ++n) _Pragma("unroll") for (int k = 0; k < 2; ++k) \
;         acc[ai][bj][m][n] = __builtin_amdgcn_mfma_f32_16x16x32_bf16(Bt[n][k], At[m][k], acc[ai][bj][m][n], 0, 0, 0); __builtin_amdgcn_s_setprio(0); } while (0)
; #define PG8_WAIT_V(n) asm volatile("s_waitcnt vmcnt(" #n ")" ::: "memory")
; #define PG8_WAIT_L(n) asm volatile("s_waitcnt lgkmcnt(" #n ")" ::: "memory")
; #define PG8_BAR __builtin_amdgcn_s_barrier()
; #define PG8_SCHED __builtin_amdgcn_sched_barrier(0)
; template <class Epi, class Sched, bool ALIGN_EPI = false, bool SP2 = false>
; __device__ __forceinline__ void gemm_phase(PG8_LAS unsigned char* lds, const Gemm g, const Sched& S, const Epi& E) {
;     ...
;             PG8_WAIT_V(8); PG8_WAIT_L(0); PG8_BAR; PG8_MMA(1, 0, At, B0); PG8_MMA(1, 1, At, B1); PG8_BAR; PG8_SCHED;
;             PG8_LDB(B0, 1, 0); PG8_LDB(B1, 1, 1); PG8_SCHED; PG8_LDA(At, 1, 0); PG8_STAGE(PG8_SA(0, 1), a2 + hstep, voffA);
;             PG8_WAIT_V(8); PG8_WAIT_L(0); PG8_BAR; PG8_MMA(0, 0, At, B0); PG8_MMA(0, 1, At, B1); PG8_BAR; PG8_SCHED;
;             PG8_LDA(At, 1, 1); PG8_STAGE(PG8_SB(1, 0), b3, voffB); PG8_STAGE(PG8_SB(1, 1), b3 + hstep, voffB); PG8_STAGE(PG8_SA(1, 0), a3, voffA);
	s_setprio 1
	s_waitcnt lgkmcnt(0)
	v_mfma_f32_16x16x32_bf16 v[62:65], v[154:157], v[188:191], v[62:65]
	v_mfma_f32_16x16x32_bf16 v[62:65], v[158:161], v[196:199], v[62:65]
	v_mfma_f32_16x16x32_bf16 v[54:57], v[162:165], v[188:191], v[54:57]
	v_mfma_f32_16x16x32_bf16 v[54:57], v[166:169], v[196:199], v[54:57]
	v_mfma_f32_16x16x32_bf16 v[46:49], v[154:157], v[200:203], v[46:49]
	v_mfma_f32_16x16x32_bf16 v[46:49], v[158:161], v[204:207], v[46:49]
	v_mfma_f32_16x16x32_bf16 v[38:41], v[162:165], v[200:203], v[38:41]
	v_mfma_f32_16x16x32_bf16 v[38:41], v[166:169], v[204:207], v[38:41]
	v_mfma_f32_16x16x32_bf16 v[30:33], v[154:157], v[208:211], v[30:33]
	v_mfma_f32_16x16x32_bf16 v[30:33], v[158:161], v[212:215], v[30:33]
	v_mfma_f32_16x16x32_bf16 v[22:25], v[162:165], v[208:211], v[22:25]
	v_mfma_f32_16x16x32_bf16 v[22:25], v[166:169], v[212:215], v[22:25]
	v_mfma_f32_16x16x32_bf16 v[14:17], v[154:157], v[216:219], v[14:17]
	v_mfma_f32_16x16x32_bf16 v[14:17], v[158:161], v[220:223], v[14:17]
	v_mfma_f32_16x16x32_bf16 v[6:9], v[162:165], v[216:219], v[6:9]
	v_mfma_f32_16x16x32_bf16 v[6:9], v[166:169], v[220:223], v[6:9]
	s_setprio 0
	s_setprio 1
	v_mfma_f32_16x16x32_bf16 v[58:61], v[170:173], v[188:191], v[58:61]
	v_mfma_f32_16x16x32_bf16 v[58:61], v[174:177], v[196:199], v[58:61]
	v_mfma_f32_16x16x32_bf16 v[50:53], v[180:183], v[188:191], v[50:53]
	v_mfma_f32_16x16x32_bf16 v[50:53], v[184:187], v[196:199], v[50:53]
	v_mfma_f32_16x16x32_bf16 v[42:45], v[170:173], v[200:203], v[42:45]
	v_mfma_f32_16x16x32_bf16 v[42:45], v[174:177], v[204:207], v[42:45]
	v_mfma_f32_16x16x32_bf16 v[34:37], v[180:183], v[200:203], v[34:37]
	v_mfma_f32_16x16x32_bf16 v[34:37], v[184:187], v[204:207], v[34:37]
	v_mfma_f32_16x16x32_bf16 v[26:29], v[170:173], v[208:211], v[26:29]
	v_mfma_f32_16x16x32_bf16 v[26:29], v[174:177], v[212:215], v[26:29]
	v_mfma_f32_16x16x32_bf16 v[18:21], v[180:183], v[208:211], v[18:21]
	v_mfma_f32_16x16x32_bf16 v[18:21], v[184:187], v[212:215], v[18:21]
	v_mfma_f32_16x16x32_bf16 v[10:13], v[170:173], v[216:219], v[10:13]
	v_mfma_f32_16x16x32_bf16 v[10:13], v[174:177], v[220:223], v[10:13]
	v_mfma_f32_16x16x32_bf16 v[2:5], v[180:183], v[216:219], v[2:5]
	v_mfma_f32_16x16x32_bf16 v[2:5], v[184:187], v[220:223], v[2:5]
	s_setprio 0
	s_barrier
	s_add_i32 s77, 0, 0x18000
	v_add_u32_e32 v138, s77, v148
	s_add_i32 s78, 0, 0x1c000
	ds_read_b128 v[154:157], v138
	ds_read_b128 v[158:161], v138 offset:1024
	ds_read_b128 v[162:165], v138 offset:2048
	ds_read_b128 v[166:169], v138 offset:3072
	v_add_u32_e32 v138, s78, v148
	ds_read_b128 v[170:173], v138
	ds_read_b128 v[174:177], v138 offset:1024
	ds_read_b128 v[180:183], v138 offset:2048
	ds_read_b128 v[184:187], v138 offset:3072
	v_lshl_add_u64 v[224:225], s[74:75], 0, v[130:131]
	s_mov_b32 m0, s28
	s_nop 0
	global_load_lds_dwordx4 v[224:225], off
	v_lshl_add_u64 v[224:225], s[74:75], 0, v[134:135]
	s_mov_b32 m0, s29
	s_nop 0
	global_load_lds_dwordx4 v[224:225], off
	s_add_u32 s74, s74, 0x4000
	s_addc_u32 s75, s75, 0
	s_mov_b32 m0, s30
	v_lshl_add_u64 v[224:225], s[74:75], 0, v[130:131]
	ds_read_b128 v[188:191], v152 offset:32768
	ds_read_b128 v[196:199], v152 offset:33792
	ds_read_b128 v[200:203], v152 offset:34816
	ds_read_b128 v[204:207], v152 offset:35840
	ds_read_b128 v[208:211], v152 offset:36864
	ds_read_b128 v[212:215], v152 offset:37888
	ds_read_b128 v[216:219], v152 offset:38912
	ds_read_b128 v[220:223], v152 offset:39936
	global_load_lds_dwordx4 v[224:225], off
	v_lshl_add_u64 v[224:225], s[74:75], 0, v[134:135]
	s_mov_b32 m0, s31
	s_nop 0
	global_load_lds_dwordx4 v[224:225], off
	s_waitcnt vmcnt(8)
	s_waitcnt lgkmcnt(0)
	s_barrier
; #define PG8_STAGE(bufoff, gbase, voff) do { _Pragma("unroll") for (int _i = 0; _i < 2; ++_i) \
;         __builtin_amdgcn_global_load_lds((const unsigned*)((const char*)(gbase) + (voff)[_i]), (PG8_LAS unsigned*)(lds + (bufoff) + ldsw + _i * 8192), 16, 0, 0); } while (0)
; #define PG8_LDA(dst, b, h) do { _Pragma("unroll") for (int m = 0; m < 4; ++m) _Pragma("unroll") for (int k = 0; k < 2; ++k) dst[m][k] = *(const PG8_LAS bf16x8*)(lds + PG8_SA(b, h) + aoff + m * 2048 + k * 1024); } while (0)
; #define PG8_MMA(ai, bj, At, Bt) do { __builtin_amdgcn_s_setprio(1); _Pragma("unroll") for (int m = 0; m < 4; ++m) _Pragma("unroll") for (int n = 0; n < 2; ++n) _Pragma("unroll") for (int k = 0; k < 2; ++k) \
;         acc[ai][bj][m][n] = __builtin_amdgcn_mfma_f32_16x16x32_bf16(Bt[n][k], At[m][k], acc[ai][bj][m][n], 0, 0, 0); __builtin_amdgcn_s_setprio(0); } while (0)
; #define PG8_WAIT_V(n) asm volatile("s_waitcnt vmcnt(" #n ")" ::: "memory")
; #define PG8_WAIT_L(n) asm volatile("s_waitcnt lgkmcnt(" #n ")" ::: "memory")
; #define PG8_BAR __builtin_amdgcn_s_barrier()
; #define PG8_SCHED __builtin_amdgcn_sched_barrier(0)
; template <class Epi, class Sched, bool ALIGN_EPI = false, bool SP2 = false>
; __device__ __forceinline__ void gemm_phase(PG8_LAS unsigned char* lds, const Gemm g, const Sched& S, const Epi& E) {
;     ...
;             PG8_WAIT_V(8); PG8_WAIT_L(0); PG8_BAR; PG8_MMA(0, 0, At, B0); PG8_MMA(0, 1, At, B1); PG8_BAR; PG8_SCHED;
;             PG8_LDA(At, 1, 1); PG8_STAGE(PG8_SB(1, 0), b3, voffB); PG8_STAGE(PG8_SB(1, 1), b3 + hstep, voffB); PG8_STAGE(PG8_SA(1, 0), a3, voffA);
;             PG8_WAIT_V(8); PG8_WAIT_L(0); PG8_BAR; PG8_MMA(1, 0, At, B0); PG8_MMA(1, 1, At, B1); PG8_BAR; PG8_SCHED;
	s_setprio 1
	s_waitcnt lgkmcnt(0)
	v_mfma_f32_16x16x32_bf16 v[126:129], v[154:157], v[188:191], v[126:129]
	v_mfma_f32_16x16x32_bf16 v[126:129], v[158:161], v[196:199], v[126:129]
	v_mfma_f32_16x16x32_bf16 v[118:121], v[162:165], v[188:191], v[118:121]
	v_mfma_f32_16x16x32_bf16 v[118:121], v[166:169], v[196:199], v[118:121]
	v_mfma_f32_16x16x32_bf16 v[110:113], v[154:157], v[200:203], v[110:113]
	v_mfma_f32_16x16x32_bf16 v[110:113], v[158:161], v[204:207], v[110:113]
	v_mfma_f32_16x16x32_bf16 v[102:105], v[162:165], v[200:203], v[102:105]
	v_mfma_f32_16x16x32_bf16 v[102:105], v[166:169], v[204:207], v[102:105]
	v_mfma_f32_16x16x32_bf16 v[94:97], v[154:157], v[208:211], v[94:97]
	v_mfma_f32_16x16x32_bf16 v[94:97], v[158:161], v[212:215], v[94:97]
	v_mfma_f32_16x16x32_bf16 v[86:89], v[162:165], v[208:211], v[86:89]
	v_mfma_f32_16x16x32_bf16 v[86:89], v[166:169], v[212:215], v[86:89]
	v_mfma_f32_16x16x32_bf16 v[78:81], v[154:157], v[216:219], v[78:81]
	v_mfma_f32_16x16x32_bf16 v[78:81], v[158:161], v[220:223], v[78:81]
	v_mfma_f32_16x16x32_bf16 v[70:73], v[162:165], v[216:219], v[70:73]
	v_mfma_f32_16x16x32_bf16 v[70:73], v[166:169], v[220:223], v[70:73]
	s_setprio 0
	s_setprio 1
	v_mfma_f32_16x16x32_bf16 v[122:125], v[170:173], v[188:191], v[122:125]
	v_mfma_f32_16x16x32_bf16 v[122:125], v[174:177], v[196:199], v[122:125]
	v_mfma_f32_16x16x32_bf16 v[114:117], v[180:183], v[188:191], v[114:117]
	v_mfma_f32_16x16x32_bf16 v[114:117], v[184:187], v[196:199], v[114:117]
	v_mfma_f32_16x16x32_bf16 v[106:109], v[170:173], v[200:203], v[106:109]
	v_mfma_f32_16x16x32_bf16 v[106:109], v[174:177], v[204:207], v[106:109]
	v_mfma_f32_16x16x32_bf16 v[98:101], v[180:183], v[200:203], v[98:101]
	v_mfma_f32_16x16x32_bf16 v[98:101], v[184:187], v[204:207], v[98:101]
	v_mfma_f32_16x16x32_bf16 v[90:93], v[170:173], v[208:211], v[90:93]
	v_mfma_f32_16x16x32_bf16 v[90:93], v[174:177], v[212:215], v[90:93]
	v_mfma_f32_16x16x32_bf16 v[82:85], v[180:183], v[208:211], v[82:85]
	v_mfma_f32_16x16x32_bf16 v[82:85], v[184:187], v[212:215], v[82:85]
	v_mfma_f32_16x16x32_bf16 v[74:77], v[170:173], v[216:219], v[74:77]
	v_mfma_f32_16x16x32_bf16 v[74:77], v[174:177], v[220:223], v[74:77]
	v_mfma_f32_16x16x32_bf16 v[66:69], v[180:183], v[216:219], v[66:69]
	v_mfma_f32_16x16x32_bf16 v[66:69], v[184:187], v[220:223], v[66:69]
	s_setprio 0
	s_barrier
	s_add_u32 s74, s72, 0x8000
	s_addc_u32 s75, s73, 0
	s_add_i32 s77, s77, s3
	v_lshl_add_u64 v[224:225], s[74:75], 0, v[132:133]
	s_mov_b32 m0, s77
	ds_read_b128 v[188:191], v152 offset:49152
	ds_read_b128 v[196:199], v152 offset:50176
	ds_read_b128 v[200:203], v152 offset:51200
	ds_read_b128 v[204:207], v152 offset:52224
	ds_read_b128 v[208:211], v152 offset:53248
	ds_read_b128 v[212:215], v152 offset:54272
	ds_read_b128 v[216:219], v152 offset:55296
	ds_read_b128 v[220:223], v152 offset:56320
	global_load_lds_dwordx4 v[224:225], off
	s_add_i32 m0, s77, 0x2000
	s_add_u32 s72, s72, 0xc000
	v_lshl_add_u64 v[224:225], s[74:75], 0, v[136:137]
	s_addc_u32 s73, s73, 0
	s_add_i32 s74, s78, s3
	global_load_lds_dwordx4 v[224:225], off
	v_lshl_add_u64 v[224:225], s[72:73], 0, v[132:133]
	s_mov_b32 m0, s74
	s_nop 0
	global_load_lds_dwordx4 v[224:225], off
	v_lshl_add_u64 v[224:225], s[72:73], 0, v[136:137]
	s_add_i32 m0, s74, 0x2000
	s_nop 0
	global_load_lds_dwordx4 v[224:225], off
	s_waitcnt vmcnt(6)
	s_waitcnt lgkmcnt(0)
	s_barrier
	s_setprio 1
	s_waitcnt lgkmcnt(0)
	v_mfma_f32_16x16x32_bf16 v[62:65], v[154:157], v[188:191], v[62:65]
	v_mfma_f32_16x16x32_bf16 v[62:65], v[158:161], v[196:199], v[62:65]
	v_mfma_f32_16x16x32_bf16 v[54:57], v[162:165], v[188:191], v[54:57]
	v_mfma_f32_16x16x32_bf16 v[54:57], v[166:169], v[196:199], v[54:57]
	v_mfma_f32_16x16x32_bf16 v[46:49], v[154:157], v[200:203], v[46:49]
	v_mfma_f32_16x16x32_bf16 v[46:49], v[158:161], v[204:207], v[46:49]
	v_mfma_f32_16x16x32_bf16 v[38:41], v[162:165], v[200:203], v[38:41]
	v_mfma_f32_16x16x32_bf16 v[38:41], v[166:169], v[204:207], v[38:41]
	v_mfma_f32_16x16x32_bf16 v[30:33], v[154:157], v[208:211], v[30:33]
	v_mfma_f32_16x16x32_bf16 v[30:33], v[158:161], v[212:215], v[30:33]
	v_mfma_f32_16x16x32_bf16 v[22:25], v[162:165], v[208:211], v[22:25]
	v_mfma_f32_16x16x32_bf16 v[22:25], v[166:169], v[212:215], v[22:25]
	v_mfma_f32_16x16x32_bf16 v[14:17], v[154:157], v[216:219], v[14:17]
	v_mfma_f32_16x16x32_bf16 v[14:17], v[158:161], v[220:223], v[14:17]
	v_mfma_f32_16x16x32_bf16 v[6:9], v[162:165], v[216:219], v[6:9]
	v_mfma_f32_16x16x32_bf16 v[6:9], v[166:169], v[220:223], v[6:9]
	s_setprio 0
	s_setprio 1
	v_mfma_f32_16x16x32_bf16 v[58:61], v[170:173], v[188:191], v[58:61]
	v_mfma_f32_16x16x32_bf16 v[58:61], v[174:177], v[196:199], v[58:61]
	v_mfma_f32_16x16x32_bf16 v[50:53], v[180:183], v[188:191], v[50:53]
	v_mfma_f32_16x16x32_bf16 v[50:53], v[184:187], v[196:199], v[50:53]
	v_mfma_f32_16x16x32_bf16 v[42:45], v[170:173], v[200:203], v[42:45]
	v_mfma_f32_16x16x32_bf16 v[42:45], v[174:177], v[204:207], v[42:45]
	v_mfma_f32_16x16x32_bf16 v[34:37], v[180:183], v[200:203], v[34:37]
	v_mfma_f32_16x16x32_bf16 v[34:37], v[184:187], v[204:207], v[34:37]
	v_mfma_f32_16x16x32_bf16 v[26:29], v[170:173], v[208:211], v[26:29]
	v_mfma_f32_16x16x32_bf16 v[26:29], v[174:177], v[212:215], v[26:29]
	v_mfma_f32_16x16x32_bf16 v[18:21], v[180:183], v[208:211], v[18:21]
	v_mfma_f32_16x16x32_bf16 v[18:21], v[184:187], v[212:215], v[18:21]
	v_mfma_f32_16x16x32_bf16 v[10:13], v[170:173], v[216:219], v[10:13]
	v_mfma_f32_16x16x32_bf16 v[10:13], v[174:177], v[220:223], v[10:13]
	v_mfma_f32_16x16x32_bf16 v[2:5], v[180:183], v[216:219], v[2:5]
	v_mfma_f32_16x16x32_bf16 v[2:5], v[184:187], v[220:223], v[2:5]
	s_setprio 0
	s_barrier
	s_add_i32 s76, s76, 2
	s_add_u32 s48, s48, 0x10000
	s_addc_u32 s49, s49, 0
	s_add_u32 s68, s68, 0x10000
	s_addc_u32 s69, s69, 0
	s_cmp_gt_u32 s76, 61
	s_cbranch_scc0 .LBB0_115
	s_and_b64 vcc, exec, s[14:15]
	s_cbranch_vccz .LBB0_118
	s_barrier

; #define PG8_STAGE(bufoff, gbase, voff) do { _Pragma("unroll") for (int _i = 0; _i < 2; ++_i) \
;         __builtin_amdgcn_global_load_lds((const unsigned*)((const char*)(gbase) + (voff)[_i]), (PG8_LAS unsigned*)(lds + (bufoff) + ldsw + _i * 8192), 16, 0, 0); } while (0)
; #define PG8_LDA(dst, b, h) do { _Pragma("unroll") for (int m = 0; m < 4; ++m) _Pragma("unroll") for (int k = 0; k < 2; ++k) dst[m][k] = *(const PG8_LAS bf16x8*)(lds + PG8_SA(b, h) + aoff + m * 2048 + k * 1024); } while (0)
; #define PG8_LDB(dst, b, h) do { _Pragma("unroll") for (int n = 0; n < 2; ++n) _Pragma("unroll") for (int k = 0; k < 2; ++k) dst[n][k] = *(const PG8_LAS bf16x8*)(lds + PG8_SB(b, h) + boff + n * 2048 + k * 1024); } while (0)
; #define PG8_MMA(ai, bj, At, Bt) do { __builtin_amdgcn_s_setprio(1); _Pragma("unroll") for (int m = 0; m < 4; ++m) _Pragma("unroll") for (int n = 0; n < 2; ++n) _Pragma("unroll") for (int k = 0; k < 2; ++k) \
;         acc[ai][bj][m][n] = __builtin_amdgcn_mfma_f32_16x16x32_bf16(Bt[n][k], At[m][k], acc[ai][bj][m][n], 0, 0, 0); __builtin_amdgcn_s_setprio(0); } while (0)
; #define PG8_WAIT_V(n) asm volatile("s_waitcnt vmcnt(" #n ")" ::: "memory")
; #define PG8_WAIT_L(n) asm volatile("s_waitcnt lgkmcnt(" #n ")" ::: "memory")
; #define PG8_BAR __builtin_amdgcn_s_barrier()
; #define PG8_SCHED __builtin_amdgcn_sched_barrier(0)
; template <class Epi, class Sched, bool ALIGN_EPI = false, bool SP2 = false>
; __device__ __forceinline__ void gemm_phase(PG8_LAS unsigned char* lds, const Gemm g, const Sched& S, const Epi& E) {
;     ...
;             PG8_LDB(B0, 0, 0); PG8_LDB(B1, 0, 1); PG8_SCHED; PG8_LDA(At, 0, 0); PG8_STAGE(PG8_SA(1, 1), a1 + hstep, voffA);
;             PG8_WAIT_V(8); PG8_WAIT_L(0); PG8_BAR; PG8_MMA(0, 0, At, B0); PG8_MMA(0, 1, At, B1); PG8_BAR; PG8_SCHED;
;             PG8_LDA(At, 0, 1); PG8_STAGE(PG8_SB(0, 0), b2, voffB); PG8_STAGE(PG8_SB(0, 1), b2 + hstep, voffB); PG8_STAGE(PG8_SA(0, 0), a2, voffA);
;             PG8_WAIT_V(8); PG8_WAIT_L(0); PG8_BAR; PG8_MMA(1, 0, At, B0); PG8_MMA(1, 1, At, B1); PG8_BAR; PG8_SCHED;
.LBB0_200:
	ds_read_b128 v[148:151], v154
	ds_read_b128 v[158:161], v154 offset:1024
	ds_read_b128 v[162:165], v154 offset:2048
	ds_read_b128 v[166:169], v154 offset:3072
	ds_read_b128 v[170:173], v155
	ds_read_b128 v[174:177], v155 offset:1024
	ds_read_b128 v[180:183], v155 offset:2048
	ds_read_b128 v[184:187], v155 offset:3072
	s_add_u32 s46, s44, 0x4000
	s_addc_u32 s47, s45, 0
	s_cmpk_eq_i32 s76, 0xa8
	s_cselect_b32 s50, s6, s46
	s_cselect_b32 s51, s7, s47
	s_cselect_b32 s48, s24, s74
	s_cselect_b32 s49, s25, s75
	s_add_u32 s46, s50, 0x8000
	s_addc_u32 s47, s51, 0
	s_sub_u32 s46, s44, 0x4000
	s_subb_u32 s47, s45, 0
	v_lshl_add_u64 v[224:225], s[46:47], 0, v[130:131]
	s_mov_b32 m0, s57
	s_nop 0
	global_load_lds_dwordx4 v[224:225], off
	v_lshl_add_u64 v[224:225], s[46:47], 0, v[134:135]
	s_mov_b32 m0, s58
	s_nop 0
	global_load_lds_dwordx4 v[224:225], off
	v_lshl_add_u64 v[224:225], s[44:45], 0, v[140:141]
	s_add_i32 m0, s26, 0xc000
	ds_read_b128 v[188:191], v156
	ds_read_b128 v[196:199], v156 offset:1024
	ds_read_b128 v[200:203], v156 offset:2048
	ds_read_b128 v[204:207], v156 offset:3072
	ds_read_b128 v[208:211], v156 offset:4096
	ds_read_b128 v[212:215], v156 offset:5120
	ds_read_b128 v[216:219], v156 offset:6144
	ds_read_b128 v[220:223], v156 offset:7168
	global_load_lds_dwordx4 v[224:225], off
	v_lshl_add_u64 v[224:225], s[44:45], 0, v[142:143]
	s_add_i32 m0, s26, 0xe000
	s_nop 0
	global_load_lds_dwordx4 v[224:225], off
	s_waitcnt vmcnt(8)
	s_waitcnt lgkmcnt(0)
	s_barrier
	s_setprio 1
	s_waitcnt lgkmcnt(0)
	v_mfma_f32_16x16x32_bf16 v[126:129], v[148:151], v[188:191], v[126:129]
	v_mfma_f32_16x16x32_bf16 v[126:129], v[158:161], v[196:199], v[126:129]
	v_mfma_f32_16x16x32_bf16 v[122:125], v[162:165], v[188:191], v[122:125]
	v_mfma_f32_16x16x32_bf16 v[122:125], v[166:169], v[196:199], v[122:125]
	v_mfma_f32_16x16x32_bf16 v[110:113], v[148:151], v[200:203], v[110:113]
	v_mfma_f32_16x16x32_bf16 v[110:113], v[158:161], v[204:207], v[110:113]
	v_mfma_f32_16x16x32_bf16 v[106:109], v[162:165], v[200:203], v[106:109]
	v_mfma_f32_16x16x32_bf16 v[106:109], v[166:169], v[204:207], v[106:109]
	v_mfma_f32_16x16x32_bf16 v[94:97], v[148:151], v[208:211], v[94:97]
	v_mfma_f32_16x16x32_bf16 v[94:97], v[158:161], v[212:215], v[94:97]
	v_mfma_f32_16x16x32_bf16 v[90:93], v[162:165], v[208:211], v[90:93]
	v_mfma_f32_16x16x32_bf16 v[90:93], v[166:169], v[212:215], v[90:93]
	v_mfma_f32_16x16x32_bf16 v[78:81], v[148:151], v[216:219], v[78:81]
	v_mfma_f32_16x16x32_bf16 v[78:81], v[158:161], v[220:223], v[78:81]
	v_mfma_f32_16x16x32_bf16 v[74:77], v[162:165], v[216:219], v[74:77]
	v_mfma_f32_16x16x32_bf16 v[74:77], v[166:169], v[220:223], v[74:77]
	s_setprio 0
	s_setprio 1
	v_mfma_f32_16x16x32_bf16 v[118:121], v[170:173], v[188:191], v[118:121]
	v_mfma_f32_16x16x32_bf16 v[118:121], v[174:177], v[196:199], v[118:121]
	v_mfma_f32_16x16x32_bf16 v[114:117], v[180:183], v[188:191], v[114:117]
	v_mfma_f32_16x16x32_bf16 v[114:117], v[184:187], v[196:199], v[114:117]
	v_mfma_f32_16x16x32_bf16 v[102:105], v[170:173], v[200:203], v[102:105]
	v_mfma_f32_16x16x32_bf16 v[102:105], v[174:177], v[204:207], v[102:105]
	v_mfma_f32_16x16x32_bf16 v[98:101], v[180:183], v[200:203], v[98:101]
	v_mfma_f32_16x16x32_bf16 v[98:101], v[184:187], v[204:207], v[98:101]
	v_mfma_f32_16x16x32_bf16 v[86:89], v[170:173], v[208:211], v[86:89]
	v_mfma_f32_16x16x32_bf16 v[86:89], v[174:177], v[212:215], v[86:89]
	v_mfma_f32_16x16x32_bf16 v[82:85], v[180:183], v[208:211], v[82:85]
	v_mfma_f32_16x16x32_bf16 v[82:85], v[184:187], v[212:215], v[82:85]
	v_mfma_f32_16x16x32_bf16 v[70:73], v[170:173], v[216:219], v[70:73]
	v_mfma_f32_16x16x32_bf16 v[70:73], v[174:177], v[220:223], v[70:73]
	v_mfma_f32_16x16x32_bf16 v[66:69], v[180:183], v[216:219], v[66:69]
	v_mfma_f32_16x16x32_bf16 v[66:69], v[184:187], v[220:223], v[66:69]
	s_setprio 0
	s_barrier
	s_add_i32 s77, s59, s3
	v_lshl_add_u64 v[224:225], s[48:49], 0, v[132:133]
	s_mov_b32 m0, s77
	ds_read_b128 v[188:191], v156 offset:16384
	ds_read_b128 v[196:199], v156 offset:17408
	ds_read_b128 v[200:203], v156 offset:18432
	ds_read_b128 v[204:207], v156 offset:19456
	ds_read_b128 v[208:211], v156 offset:20480
	ds_read_b128 v[212:215], v156 offset:21504
	ds_read_b128 v[216:219], v156 offset:22528
	ds_read_b128 v[220:223], v156 offset:23552
	global_load_lds_dwordx4 v[224:225], off
	s_add_i32 m0, s77, 0x2000
	s_add_u32 s78, s48, 0x4000
	v_lshl_add_u64 v[224:225], s[48:49], 0, v[136:137]
	s_addc_u32 s79, s49, 0
	s_add_i32 s77, s61, s3
	global_load_lds_dwordx4 v[224:225], off
	v_lshl_add_u64 v[224:225], s[78:79], 0, v[132:133]
	s_mov_b32 m0, s77
	s_nop 0
	global_load_lds_dwordx4 v[224:225], off
	v_lshl_add_u64 v[224:225], s[78:79], 0, v[136:137]
	s_add_i32 m0, s77, 0x2000
	s_nop 0
	global_load_lds_dwordx4 v[224:225], off
	s_waitcnt vmcnt(6)
	s_waitcnt lgkmcnt(0)
	s_barrier
; #define PG8_STAGE(bufoff, gbase, voff) do { _Pragma("unroll") for (int _i = 0; _i < 2; ++_i) \
;         __builtin_amdgcn_global_load_lds((const unsigned*)((const char*)(gbase) + (voff)[_i]), (PG8_LAS unsigned*)(lds + (bufoff) + ldsw + _i * 8192), 16, 0, 0); } while (0)
; #define PG8_LDA(dst, b, h) do { _Pragma("unroll") for (int m = 0; m < 4; ++m) _Pragma("unroll") for (int k = 0; k < 2; ++k) dst[m][k] = *(const PG8_LAS bf16x8*)(lds + PG8_SA(b, h) + aoff + m * 2048 + k * 1024); } while (0)
; #define PG8_LDB(dst, b, h) do { _Pragma("unroll") for (int n = 0; n < 2; ++n) _Pragma("unroll") for (int k = 0; k < 2; ++k) dst[n][k] = *(const PG8_LAS bf16x8*)(lds + PG8_SB(b, h) + boff + n * 2048 + k * 1024); } while (0)
; #define PG8_MMA(ai, bj, At, Bt) do { __builtin_amdgcn_s_setprio(1); _Pragma("unroll") for (int m = 0; m < 4; ++m) _Pragma("unroll") for (int n = 0; n < 2; ++n) _Pragma("unroll") for (int k = 0; k < 2; ++k) \
;         acc[ai][bj][m][n] = __builtin_amdgcn_mfma_f32_16x16x32_bf16(Bt[n][k], At[m][k], acc[ai][bj][m][n], 0, 0, 0); __builtin_amdgcn_s_setprio(0); } while (0)
; #define PG8_WAIT_V(n) asm volatile("s_waitcnt vmcnt(" #n ")" ::: "memory")
; #define PG8_WAIT_L(n) asm volatile("s_waitcnt lgkmcnt(" #n ")" ::: "memory")
; #define PG8_BAR __builtin_amdgcn_s_barrier()
; #define PG8_SCHED __builtin_amdgcn_sched_barrier(0)
; template <class Epi, class Sched, bool ALIGN_EPI = false, bool SP2 = false>
; __device__ __forceinline__ void gemm_phase(PG8_LAS unsigned char* lds, const Gemm g, const Sched& S, const Epi& E) {
;     ...
;             PG8_WAIT_V(8); PG8_WAIT_L(0); PG8_BAR; PG8_MMA(1, 0, At, B0); PG8_MMA(1, 1, At, B1); PG8_BAR; PG8_SCHED;
;             PG8_LDB(B0, 1, 0); PG8_LDB(B1, 1, 1); PG8_SCHED; PG8_LDA(At, 1, 0); PG8_STAGE(PG8_SA(0, 1), a2 + hstep, voffA);
;             PG8_WAIT_V(8); PG8_WAIT_L(0); PG8_BAR; PG8_MMA(0, 0, At, B0); PG8_MMA(0, 1, At, B1); PG8_BAR; PG8_SCHED;
;             PG8_LDA(At, 1, 1); PG8_STAGE(PG8_SB(1, 0), b3, voffB); PG8_STAGE(PG8_SB(1, 1), b3 + hstep, voffB); PG8_STAGE(PG8_SA(1, 0), a3, voffA);
	s_setprio 1
	s_waitcnt lgkmcnt(0)
	v_mfma_f32_16x16x32_bf16 v[62:65], v[148:151], v[188:191], v[62:65]
	v_mfma_f32_16x16x32_bf16 v[62:65], v[158:161], v[196:199], v[62:65]
	v_mfma_f32_16x16x32_bf16 v[58:61], v[162:165], v[188:191], v[58:61]
	v_mfma_f32_16x16x32_bf16 v[58:61], v[166:169], v[196:199], v[58:61]
	v_mfma_f32_16x16x32_bf16 v[46:49], v[148:151], v[200:203], v[46:49]
	v_mfma_f32_16x16x32_bf16 v[46:49], v[158:161], v[204:207], v[46:49]
	v_mfma_f32_16x16x32_bf16 v[42:45], v[162:165], v[200:203], v[42:45]
	v_mfma_f32_16x16x32_bf16 v[42:45], v[166:169], v[204:207], v[42:45]
	v_mfma_f32_16x16x32_bf16 v[30:33], v[148:151], v[208:211], v[30:33]
	v_mfma_f32_16x16x32_bf16 v[30:33], v[158:161], v[212:215], v[30:33]
	v_mfma_f32_16x16x32_bf16 v[26:29], v[162:165], v[208:211], v[26:29]
	v_mfma_f32_16x16x32_bf16 v[26:29], v[166:169], v[212:215], v[26:29]
	v_mfma_f32_16x16x32_bf16 v[14:17], v[148:151], v[216:219], v[14:17]
	v_mfma_f32_16x16x32_bf16 v[14:17], v[158:161], v[220:223], v[14:17]
	v_mfma_f32_16x16x32_bf16 v[10:13], v[162:165], v[216:219], v[10:13]
	v_mfma_f32_16x16x32_bf16 v[10:13], v[166:169], v[220:223], v[10:13]
	s_setprio 0
	s_setprio 1
	v_mfma_f32_16x16x32_bf16 v[54:57], v[170:173], v[188:191], v[54:57]
	v_mfma_f32_16x16x32_bf16 v[54:57], v[174:177], v[196:199], v[54:57]
	v_mfma_f32_16x16x32_bf16 v[50:53], v[180:183], v[188:191], v[50:53]
	v_mfma_f32_16x16x32_bf16 v[50:53], v[184:187], v[196:199], v[50:53]
	v_mfma_f32_16x16x32_bf16 v[38:41], v[170:173], v[200:203], v[38:41]
	v_mfma_f32_16x16x32_bf16 v[38:41], v[174:177], v[204:207], v[38:41]
	v_mfma_f32_16x16x32_bf16 v[34:37], v[180:183], v[200:203], v[34:37]
	v_mfma_f32_16x16x32_bf16 v[34:37], v[184:187], v[204:207], v[34:37]
	v_mfma_f32_16x16x32_bf16 v[22:25], v[170:173], v[208:211], v[22:25]
	v_mfma_f32_16x16x32_bf16 v[22:25], v[174:177], v[212:215], v[22:25]
	v_mfma_f32_16x16x32_bf16 v[18:21], v[180:183], v[208:211], v[18:21]
	v_mfma_f32_16x16x32_bf16 v[18:21], v[184:187], v[212:215], v[18:21]
	v_mfma_f32_16x16x32_bf16 v[6:9], v[170:173], v[216:219], v[6:9]
	v_mfma_f32_16x16x32_bf16 v[6:9], v[174:177], v[220:223], v[6:9]
	v_mfma_f32_16x16x32_bf16 v[2:5], v[180:183], v[216:219], v[2:5]
	v_mfma_f32_16x16x32_bf16 v[2:5], v[184:187], v[220:223], v[2:5]
	s_setprio 0
	s_barrier
	s_add_i32 s77, 0, 0x18000
	v_add_u32_e32 v138, s77, v153
	s_add_i32 s78, 0, 0x1c000
	ds_read_b128 v[148:151], v138
	ds_read_b128 v[158:161], v138 offset:1024
	ds_read_b128 v[162:165], v138 offset:2048
	ds_read_b128 v[166:169], v138 offset:3072
	v_add_u32_e32 v138, s78, v153
	ds_read_b128 v[170:173], v138
	ds_read_b128 v[174:177], v138 offset:1024
	ds_read_b128 v[180:183], v138 offset:2048
	ds_read_b128 v[184:187], v138 offset:3072
	v_lshl_add_u64 v[224:225], s[50:51], 0, v[130:131]
	s_mov_b32 m0, s26
	s_nop 0
	global_load_lds_dwordx4 v[224:225], off
	v_lshl_add_u64 v[224:225], s[50:51], 0, v[134:135]
	s_mov_b32 m0, s27
	s_nop 0
	global_load_lds_dwordx4 v[224:225], off
	s_add_u32 s50, s50, 0x4000
	s_addc_u32 s51, s51, 0
	s_mov_b32 m0, s28
	v_lshl_add_u64 v[224:225], s[50:51], 0, v[130:131]
	ds_read_b128 v[188:191], v156 offset:32768
	ds_read_b128 v[196:199], v156 offset:33792
	ds_read_b128 v[200:203], v156 offset:34816
	ds_read_b128 v[204:207], v156 offset:35840
	ds_read_b128 v[208:211], v156 offset:36864
	ds_read_b128 v[212:215], v156 offset:37888
	ds_read_b128 v[216:219], v156 offset:38912
	ds_read_b128 v[220:223], v156 offset:39936
	global_load_lds_dwordx4 v[224:225], off
	v_lshl_add_u64 v[224:225], s[50:51], 0, v[134:135]
	s_mov_b32 m0, s29
	s_nop 0
	global_load_lds_dwordx4 v[224:225], off
	s_waitcnt vmcnt(8)
	s_waitcnt lgkmcnt(0)
	s_barrier
; #define PG8_STAGE(bufoff, gbase, voff) do { _Pragma("unroll") for (int _i = 0; _i < 2; ++_i) \
;         __builtin_amdgcn_global_load_lds((const unsigned*)((const char*)(gbase) + (voff)[_i]), (PG8_LAS unsigned*)(lds + (bufoff) + ldsw + _i * 8192), 16, 0, 0); } while (0)
; #define PG8_LDA(dst, b, h) do { _Pragma("unroll") for (int m = 0; m < 4; ++m) _Pragma("unroll") for (int k = 0; k < 2; ++k) dst[m][k] = *(const PG8_LAS bf16x8*)(lds + PG8_SA(b, h) + aoff + m * 2048 + k * 1024); } while (0)
; #define PG8_MMA(ai, bj, At, Bt) do { __builtin_amdgcn_s_setprio(1); _Pragma("unroll") for (int m = 0; m < 4; ++m) _Pragma("unroll") for (int n = 0; n < 2; ++n) _Pragma("unroll") for (int k = 0; k < 2; ++k) \
;         acc[ai][bj][m][n] = __builtin_amdgcn_mfma_f32_16x16x32_bf16(Bt[n][k], At[m][k], acc[ai][bj][m][n], 0, 0, 0); __builtin_amdgcn_s_setprio(0); } while (0)
; #define PG8_WAIT_V(n) asm volatile("s_waitcnt vmcnt(" #n ")" ::: "memory")
; #define PG8_WAIT_L(n) asm volatile("s_waitcnt lgkmcnt(" #n ")" ::: "memory")
; #define PG8_BAR __builtin_amdgcn_s_barrier()
; #define PG8_SCHED __builtin_amdgcn_sched_barrier(0)
; template <class Epi, class Sched, bool ALIGN_EPI = false, bool SP2 = false>
; __device__ __forceinline__ void gemm_phase(PG8_LAS unsigned char* lds, const Gemm g, const Sched& S, const Epi& E) {
;     ...
;             PG8_WAIT_V(8); PG8_WAIT_L(0); PG8_BAR; PG8_MMA(0, 0, At, B0); PG8_MMA(0, 1, At, B1); PG8_BAR; PG8_SCHED;
;             PG8_LDA(At, 1, 1); PG8_STAGE(PG8_SB(1, 0), b3, voffB); PG8_STAGE(PG8_SB(1, 1), b3 + hstep, voffB); PG8_STAGE(PG8_SA(1, 0), a3, voffA);
;             PG8_WAIT_V(8); PG8_WAIT_L(0); PG8_BAR; PG8_MMA(1, 0, At, B0); PG8_MMA(1, 1, At, B1); PG8_BAR; PG8_SCHED;
	s_setprio 1
	s_waitcnt lgkmcnt(0)
	v_mfma_f32_16x16x32_bf16 v[126:129], v[148:151], v[188:191], v[126:129]
	v_mfma_f32_16x16x32_bf16 v[126:129], v[158:161], v[196:199], v[126:129]
	v_mfma_f32_16x16x32_bf16 v[122:125], v[162:165], v[188:191], v[122:125]
	v_mfma_f32_16x16x32_bf16 v[122:125], v[166:169], v[196:199], v[122:125]
	v_mfma_f32_16x16x32_bf16 v[110:113], v[148:151], v[200:203], v[110:113]
	v_mfma_f32_16x16x32_bf16 v[110:113], v[158:161], v[204:207], v[110:113]
	v_mfma_f32_16x16x32_bf16 v[106:109], v[162:165], v[200:203], v[106:109]
	v_mfma_f32_16x16x32_bf16 v[106:109], v[166:169], v[204:207], v[106:109]
	v_mfma_f32_16x16x32_bf16 v[94:97], v[148:151], v[208:211], v[94:97]
	v_mfma_f32_16x16x32_bf16 v[94:97], v[158:161], v[212:215], v[94:97]
	v_mfma_f32_16x16x32_bf16 v[90:93], v[162:165], v[208:211], v[90:93]
	v_mfma_f32_16x16x32_bf16 v[90:93], v[166:169], v[212:215], v[90:93]
	v_mfma_f32_16x16x32_bf16 v[78:81], v[148:151], v[216:219], v[78:81]
	v_mfma_f32_16x16x32_bf16 v[78:81], v[158:161], v[220:223], v[78:81]
	v_mfma_f32_16x16x32_bf16 v[74:77], v[162:165], v[216:219], v[74:77]
	v_mfma_f32_16x16x32_bf16 v[74:77], v[166:169], v[220:223], v[74:77]
	s_setprio 0
	s_setprio 1
	v_mfma_f32_16x16x32_bf16 v[118:121], v[170:173], v[188:191], v[118:121]
	v_mfma_f32_16x16x32_bf16 v[118:121], v[174:177], v[196:199], v[118:121]
	v_mfma_f32_16x16x32_bf16 v[114:117], v[180:183], v[188:191], v[114:117]
	v_mfma_f32_16x16x32_bf16 v[114:117], v[184:187], v[196:199], v[114:117]
	v_mfma_f32_16x16x32_bf16 v[102:105], v[170:173], v[200:203], v[102:105]
	v_mfma_f32_16x16x32_bf16 v[102:105], v[174:177], v[204:207], v[102:105]
	v_mfma_f32_16x16x32_bf16 v[98:101], v[180:183], v[200:203], v[98:101]
	v_mfma_f32_16x16x32_bf16 v[98:101], v[184:187], v[204:207], v[98:101]
	v_mfma_f32_16x16x32_bf16 v[86:89], v[170:173], v[208:211], v[86:89]
	v_mfma_f32_16x16x32_bf16 v[86:89], v[174:177], v[212:215], v[86:89]
	v_mfma_f32_16x16x32_bf16 v[82:85], v[180:183], v[208:211], v[82:85]
	v_mfma_f32_16x16x32_bf16 v[82:85], v[184:187], v[212:215], v[82:85]
	v_mfma_f32_16x16x32_bf16 v[70:73], v[170:173], v[216:219], v[70:73]
	v_mfma_f32_16x16x32_bf16 v[70:73], v[174:177], v[220:223], v[70:73]
	v_mfma_f32_16x16x32_bf16 v[66:69], v[180:183], v[216:219], v[66:69]
	v_mfma_f32_16x16x32_bf16 v[66:69], v[184:187], v[220:223], v[66:69]
	s_setprio 0
	s_barrier
	s_add_u32 s50, s48, 0x8000
	s_addc_u32 s51, s49, 0
	s_add_i32 s77, s77, s3
	v_lshl_add_u64 v[224:225], s[50:51], 0, v[132:133]
	s_mov_b32 m0, s77
	ds_read_b128 v[188:191], v156 offset:49152
	ds_read_b128 v[196:199], v156 offset:50176
	ds_read_b128 v[200:203], v156 offset:51200
	ds_read_b128 v[204:207], v156 offset:52224
	ds_read_b128 v[208:211], v156 offset:53248
	ds_read_b128 v[212:215], v156 offset:54272
	ds_read_b128 v[216:219], v156 offset:55296
	ds_read_b128 v[220:223], v156 offset:56320
	global_load_lds_dwordx4 v[224:225], off
	s_add_i32 m0, s77, 0x2000
	s_add_u32 s48, s48, 0xc000
	v_lshl_add_u64 v[224:225], s[50:51], 0, v[136:137]
	s_addc_u32 s49, s49, 0
	s_add_i32 s50, s78, s3
	global_load_lds_dwordx4 v[224:225], off
	v_lshl_add_u64 v[224:225], s[48:49], 0, v[132:133]
	s_mov_b32 m0, s50
	s_nop 0
	global_load_lds_dwordx4 v[224:225], off
	v_lshl_add_u64 v[224:225], s[48:49], 0, v[136:137]
	s_add_i32 m0, s50, 0x2000
	s_nop 0
	global_load_lds_dwordx4 v[224:225], off
	s_waitcnt vmcnt(6)
	s_waitcnt lgkmcnt(0)
	s_barrier
	s_setprio 1
	s_waitcnt lgkmcnt(0)
	v_mfma_f32_16x16x32_bf16 v[62:65], v[148:151], v[188:191], v[62:65]
	v_mfma_f32_16x16x32_bf16 v[62:65], v[158:161], v[196:199], v[62:65]
	v_mfma_f32_16x16x32_bf16 v[58:61], v[162:165], v[188:191], v[58:61]
	v_mfma_f32_16x16x32_bf16 v[58:61], v[166:169], v[196:199], v[58:61]
	v_mfma_f32_16x16x32_bf16 v[46:49], v[148:151], v[200:203], v[46:49]
	v_mfma_f32_16x16x32_bf16 v[46:49], v[158:161], v[204:207], v[46:49]
	v_mfma_f32_16x16x32_bf16 v[42:45], v[162:165], v[200:203], v[42:45]
	v_mfma_f32_16x16x32_bf16 v[42:45], v[166:169], v[204:207], v[42:45]
	v_mfma_f32_16x16x32_bf16 v[30:33], v[148:151], v[208:211], v[30:33]
	v_mfma_f32_16x16x32_bf16 v[30:33], v[158:161], v[212:215], v[30:33]
	v_mfma_f32_16x16x32_bf16 v[26:29], v[162:165], v[208:211], v[26:29]
	v_mfma_f32_16x16x32_bf16 v[26:29], v[166:169], v[212:215], v[26:29]
	v_mfma_f32_16x16x32_bf16 v[14:17], v[148:151], v[216:219], v[14:17]
	v_mfma_f32_16x16x32_bf16 v[14:17], v[158:161], v[220:223], v[14:17]
	v_mfma_f32_16x16x32_bf16 v[10:13], v[162:165], v[216:219], v[10:13]
	v_mfma_f32_16x16x32_bf16 v[10:13], v[166:169], v[220:223], v[10:13]
	s_setprio 0
	s_setprio 1
	v_mfma_f32_16x16x32_bf16 v[54:57], v[170:173], v[188:191], v[54:57]
	v_mfma_f32_16x16x32_bf16 v[54:57], v[174:177], v[196:199], v[54:57]
	v_mfma_f32_16x16x32_bf16 v[50:53], v[180:183], v[188:191], v[50:53]
	v_mfma_f32_16x16x32_bf16 v[50:53], v[184:187], v[196:199], v[50:53]
	v_mfma_f32_16x16x32_bf16 v[38:41], v[170:173], v[200:203], v[38:41]
	v_mfma_f32_16x16x32_bf16 v[38:41], v[174:177], v[204:207], v[38:41]
	v_mfma_f32_16x16x32_bf16 v[34:37], v[180:183], v[200:203], v[34:37]
	v_mfma_f32_16x16x32_bf16 v[34:37], v[184:187], v[204:207], v[34:37]
	v_mfma_f32_16x16x32_bf16 v[22:25], v[170:173], v[208:211], v[22:25]
	v_mfma_f32_16x16x32_bf16 v[22:25], v[174:177], v[212:215], v[22:25]
	v_mfma_f32_16x16x32_bf16 v[18:21], v[180:183], v[208:211], v[18:21]
	v_mfma_f32_16x16x32_bf16 v[18:21], v[184:187], v[212:215], v[18:21]
	v_mfma_f32_16x16x32_bf16 v[6:9], v[170:173], v[216:219], v[6:9]
	v_mfma_f32_16x16x32_bf16 v[6:9], v[174:177], v[220:223], v[6:9]
	v_mfma_f32_16x16x32_bf16 v[2:5], v[180:183], v[216:219], v[2:5]
	v_mfma_f32_16x16x32_bf16 v[2:5], v[184:187], v[220:223], v[2:5]
	s_setprio 0
	s_barrier
	s_add_i32 s76, s76, 2
	s_add_u32 s44, s44, 0x10000
	s_addc_u32 s45, s45, 0
	s_add_u32 s74, s74, 0x10000
	s_addc_u32 s75, s75, 0
	s_cmpk_gt_u32 s76, 0xa9
	s_cbranch_scc0 .LBB0_200
	s_and_b64 vcc, exec, s[18:19]
	s_cbranch_vccz .LBB0_203
	s_barrier

; #define PG8_STAGE(bufoff, gbase, voff) do { _Pragma("unroll") for (int _i = 0; _i < 2; ++_i) \
;         __builtin_amdgcn_global_load_lds((const unsigned*)((const char*)(gbase) + (voff)[_i]), (PG8_LAS unsigned*)(lds + (bufoff) + ldsw + _i * 8192), 16, 0, 0); } while (0)
; #define PG8_LDA(dst, b, h) do { _Pragma("unroll") for (int m = 0; m < 4; ++m) _Pragma("unroll") for (int k = 0; k < 2; ++k) dst[m][k] = *(const PG8_LAS bf16x8*)(lds + PG8_SA(b, h) + aoff + m * 2048 + k * 1024); } while (0)
; #define PG8_LDB(dst, b, h) do { _Pragma("unroll") for (int n = 0; n < 2; ++n) _Pragma("unroll") for (int k = 0; k < 2; ++k) dst[n][k] = *(const PG8_LAS bf16x8*)(lds + PG8_SB(b, h) + boff + n * 2048 + k * 1024); } while (0)
; #define PG8_MMA(ai, bj, At, Bt) do { __builtin_amdgcn_s_setprio(1); _Pragma("unroll") for (int m = 0; m < 4; ++m) _Pragma("unroll") for (int n = 0; n < 2; ++n) _Pragma("unroll") for (int k = 0; k < 2; ++k) \
;         acc[ai][bj][m][n] = __builtin_amdgcn_mfma_f32_16x16x32_bf16(Bt[n][k], At[m][k], acc[ai][bj][m][n], 0, 0, 0); __builtin_amdgcn_s_setprio(0); } while (0)
; #define PG8_WAIT_V(n) asm volatile("s_waitcnt vmcnt(" #n ")" ::: "memory")
; #define PG8_WAIT_L(n) asm volatile("s_waitcnt lgkmcnt(" #n ")" ::: "memory")
; #define PG8_BAR __builtin_amdgcn_s_barrier()
; #define PG8_SCHED __builtin_amdgcn_sched_barrier(0)
; template <class Epi, class Sched, bool ALIGN_EPI = false, bool SP2 = false>
; __device__ __forceinline__ void gemm_phase(PG8_LAS unsigned char* lds, const Gemm g, const Sched& S, const Epi& E) {
;     ...
;             PG8_LDB(B0, 0, 0); PG8_LDB(B1, 0, 1); PG8_SCHED; PG8_LDA(At, 0, 0); PG8_STAGE(PG8_SA(1, 1), a1 + hstep, voffA);
;             PG8_WAIT_V(8); PG8_WAIT_L(0); PG8_BAR; PG8_MMA(0, 0, At, B0); PG8_MMA(0, 1, At, B1); PG8_BAR; PG8_SCHED;
;             PG8_LDA(At, 0, 1); PG8_STAGE(PG8_SB(0, 0), b2, voffB); PG8_STAGE(PG8_SB(0, 1), b2 + hstep, voffB); PG8_STAGE(PG8_SA(0, 0), a2, voffA);
;             PG8_WAIT_V(8); PG8_WAIT_L(0); PG8_BAR; PG8_MMA(1, 0, At, B0); PG8_MMA(1, 1, At, B1); PG8_BAR; PG8_SCHED;
.LBB0_290:
	ds_read_b128 v[146:149], v162
	ds_read_b128 v[150:153], v162 offset:1024
	ds_read_b128 v[154:157], v162 offset:2048
	ds_read_b128 v[168:171], v162 offset:3072
	ds_read_b128 v[172:175], v163
	ds_read_b128 v[180:183], v163 offset:1024
	ds_read_b128 v[184:187], v163 offset:2048
	ds_read_b128 v[188:191], v163 offset:3072
	s_add_u32 s59, s72, 0x4000
	s_addc_u32 s62, s73, 0
	s_cmp_eq_u32 s58, 60
	s_cselect_b32 s78, s19, s59
	s_cselect_b32 s79, s5, s62
	s_cselect_b32 s76, s26, s33
	s_cselect_b32 s77, s17, s56
	s_add_u32 s74, s78, 0x8000
	s_addc_u32 s75, s79, 0
	s_sub_u32 s74, s72, 0x4000
	s_subb_u32 s75, s73, 0
	v_lshl_add_u64 v[158:159], s[74:75], 0, v[130:131]
	s_mov_b32 m0, s51
	s_nop 0
	global_load_lds_dwordx4 v[158:159], off
	v_lshl_add_u64 v[158:159], s[74:75], 0, v[134:135]
	s_mov_b32 m0, s57
	s_nop 0
	global_load_lds_dwordx4 v[158:159], off
	v_lshl_add_u64 v[158:159], s[72:73], 0, v[138:139]
	s_add_i32 m0, s15, 0xc000
	ds_read_b128 v[198:201], v164
	ds_read_b128 v[202:205], v164 offset:1024
	ds_read_b128 v[206:209], v164 offset:2048
	ds_read_b128 v[210:213], v164 offset:3072
	ds_read_b128 v[214:217], v164 offset:4096
	ds_read_b128 v[218:221], v164 offset:5120
	ds_read_b128 v[222:225], v164 offset:6144
	ds_read_b128 v[226:229], v164 offset:7168
	global_load_lds_dwordx4 v[158:159], off
	v_lshl_add_u64 v[158:159], s[72:73], 0, v[140:141]
	s_add_i32 m0, s15, 0xe000
	s_nop 0
	global_load_lds_dwordx4 v[158:159], off
	s_waitcnt vmcnt(8)
	s_waitcnt lgkmcnt(0)
	s_barrier
	s_setprio 1
	s_waitcnt lgkmcnt(0)
	v_mfma_f32_16x16x32_bf16 v[126:129], v[146:149], v[198:201], v[126:129]
	v_mfma_f32_16x16x32_bf16 v[126:129], v[150:153], v[202:205], v[126:129]
	v_mfma_f32_16x16x32_bf16 v[122:125], v[154:157], v[198:201], v[122:125]
	v_mfma_f32_16x16x32_bf16 v[122:125], v[168:171], v[202:205], v[122:125]
	v_mfma_f32_16x16x32_bf16 v[110:113], v[146:149], v[206:209], v[110:113]
	v_mfma_f32_16x16x32_bf16 v[110:113], v[150:153], v[210:213], v[110:113]
	v_mfma_f32_16x16x32_bf16 v[106:109], v[154:157], v[206:209], v[106:109]
	v_mfma_f32_16x16x32_bf16 v[106:109], v[168:171], v[210:213], v[106:109]
	v_mfma_f32_16x16x32_bf16 v[94:97], v[146:149], v[214:217], v[94:97]
	v_mfma_f32_16x16x32_bf16 v[94:97], v[150:153], v[218:221], v[94:97]
	v_mfma_f32_16x16x32_bf16 v[90:93], v[154:157], v[214:217], v[90:93]
	v_mfma_f32_16x16x32_bf16 v[90:93], v[168:171], v[218:221], v[90:93]
	v_mfma_f32_16x16x32_bf16 v[78:81], v[146:149], v[222:225], v[78:81]
	v_mfma_f32_16x16x32_bf16 v[78:81], v[150:153], v[226:229], v[78:81]
	v_mfma_f32_16x16x32_bf16 v[74:77], v[154:157], v[222:225], v[74:77]
	v_mfma_f32_16x16x32_bf16 v[74:77], v[168:171], v[226:229], v[74:77]
	s_setprio 0
	s_setprio 1
	v_mfma_f32_16x16x32_bf16 v[118:121], v[172:175], v[198:201], v[118:121]
	v_mfma_f32_16x16x32_bf16 v[118:121], v[180:183], v[202:205], v[118:121]
	v_mfma_f32_16x16x32_bf16 v[114:117], v[184:187], v[198:201], v[114:117]
	v_mfma_f32_16x16x32_bf16 v[114:117], v[188:191], v[202:205], v[114:117]
	v_mfma_f32_16x16x32_bf16 v[102:105], v[172:175], v[206:209], v[102:105]
	v_mfma_f32_16x16x32_bf16 v[102:105], v[180:183], v[210:213], v[102:105]
	v_mfma_f32_16x16x32_bf16 v[98:101], v[184:187], v[206:209], v[98:101]
	v_mfma_f32_16x16x32_bf16 v[98:101], v[188:191], v[210:213], v[98:101]
	v_mfma_f32_16x16x32_bf16 v[86:89], v[172:175], v[214:217], v[86:89]
	v_mfma_f32_16x16x32_bf16 v[86:89], v[180:183], v[218:221], v[86:89]
	v_mfma_f32_16x16x32_bf16 v[82:85], v[184:187], v[214:217], v[82:85]
	v_mfma_f32_16x16x32_bf16 v[82:85], v[188:191], v[218:221], v[82:85]
	v_mfma_f32_16x16x32_bf16 v[70:73], v[172:175], v[222:225], v[70:73]
	v_mfma_f32_16x16x32_bf16 v[70:73], v[180:183], v[226:229], v[70:73]
	v_mfma_f32_16x16x32_bf16 v[66:69], v[184:187], v[222:225], v[66:69]
	v_mfma_f32_16x16x32_bf16 v[66:69], v[188:191], v[226:229], v[66:69]
	s_setprio 0
	s_barrier
	s_add_i32 s59, s81, s3
	v_lshl_add_u64 v[158:159], s[76:77], 0, v[132:133]
	s_mov_b32 m0, s59
	ds_read_b128 v[198:201], v164 offset:16384
	ds_read_b128 v[202:205], v164 offset:17408
	ds_read_b128 v[206:209], v164 offset:18432
	ds_read_b128 v[210:213], v164 offset:19456
	ds_read_b128 v[214:217], v164 offset:20480
	ds_read_b128 v[218:221], v164 offset:21504
	ds_read_b128 v[222:225], v164 offset:22528
	ds_read_b128 v[226:229], v164 offset:23552
	global_load_lds_dwordx4 v[158:159], off
	s_add_i32 m0, s59, 0x2000
	s_add_u32 s62, s76, 0x4000
	v_lshl_add_u64 v[158:159], s[76:77], 0, v[136:137]
	s_addc_u32 s63, s77, 0
	s_add_i32 s59, s82, s3
	global_load_lds_dwordx4 v[158:159], off
	v_lshl_add_u64 v[158:159], s[62:63], 0, v[132:133]
	s_mov_b32 m0, s59
	s_nop 0
	global_load_lds_dwordx4 v[158:159], off
	v_lshl_add_u64 v[158:159], s[62:63], 0, v[136:137]
	s_add_i32 m0, s59, 0x2000
	s_nop 0
	global_load_lds_dwordx4 v[158:159], off
	s_waitcnt vmcnt(6)
	s_waitcnt lgkmcnt(0)
	s_barrier
; #define PG8_STAGE(bufoff, gbase, voff) do { _Pragma("unroll") for (int _i = 0; _i < 2; ++_i) \
;         __builtin_amdgcn_global_load_lds((const unsigned*)((const char*)(gbase) + (voff)[_i]), (PG8_LAS unsigned*)(lds + (bufoff) + ldsw + _i * 8192), 16, 0, 0); } while (0)
; #define PG8_LDA(dst, b, h) do { _Pragma("unroll") for (int m = 0; m < 4; ++m) _Pragma("unroll") for (int k = 0; k < 2; ++k) dst[m][k] = *(const PG8_LAS bf16x8*)(lds + PG8_SA(b, h) + aoff + m * 2048 + k * 1024); } while (0)
; #define PG8_LDB(dst, b, h) do { _Pragma("unroll") for (int n = 0; n < 2; ++n) _Pragma("unroll") for (int k = 0; k < 2; ++k) dst[n][k] = *(const PG8_LAS bf16x8*)(lds + PG8_SB(b, h) + boff + n * 2048 + k * 1024); } while (0)
; #define PG8_MMA(ai, bj, At, Bt) do { __builtin_amdgcn_s_setprio(1); _Pragma("unroll") for (int m = 0; m < 4; ++m) _Pragma("unroll") for (int n = 0; n < 2; ++n) _Pragma("unroll") for (int k = 0; k < 2; ++k) \
;         acc[ai][bj][m][n] = __builtin_amdgcn_mfma_f32_16x16x32_bf16(Bt[n][k], At[m][k], acc[ai][bj][m][n], 0, 0, 0); __builtin_amdgcn_s_setprio(0); } while (0)
; #define PG8_WAIT_V(n) asm volatile("s_waitcnt vmcnt(" #n ")" ::: "memory")
; #define PG8_WAIT_L(n) asm volatile("s_waitcnt lgkmcnt(" #n ")" ::: "memory")
; #define PG8_BAR __builtin_amdgcn_s_barrier()
; #define PG8_SCHED __builtin_amdgcn_sched_barrier(0)
; template <class Epi, class Sched, bool ALIGN_EPI = false, bool SP2 = false>
; __device__ __forceinline__ void gemm_phase(PG8_LAS unsigned char* lds, const Gemm g, const Sched& S, const Epi& E) {
;     ...
;             PG8_WAIT_V(8); PG8_WAIT_L(0); PG8_BAR; PG8_MMA(1, 0, At, B0); PG8_MMA(1, 1, At, B1); PG8_BAR; PG8_SCHED;
;             PG8_LDB(B0, 1, 0); PG8_LDB(B1, 1, 1); PG8_SCHED; PG8_LDA(At, 1, 0); PG8_STAGE(PG8_SA(0, 1), a2 + hstep, voffA);
;             PG8_WAIT_V(8); PG8_WAIT_L(0); PG8_BAR; PG8_MMA(0, 0, At, B0); PG8_MMA(0, 1, At, B1); PG8_BAR; PG8_SCHED;
;             PG8_LDA(At, 1, 1); PG8_STAGE(PG8_SB(1, 0), b3, voffB); PG8_STAGE(PG8_SB(1, 1), b3 + hstep, voffB); PG8_STAGE(PG8_SA(1, 0), a3, voffA);
	s_setprio 1
	s_waitcnt lgkmcnt(0)
	v_mfma_f32_16x16x32_bf16 v[62:65], v[146:149], v[198:201], v[62:65]
	v_mfma_f32_16x16x32_bf16 v[62:65], v[150:153], v[202:205], v[62:65]
	v_mfma_f32_16x16x32_bf16 v[58:61], v[154:157], v[198:201], v[58:61]
	v_mfma_f32_16x16x32_bf16 v[58:61], v[168:171], v[202:205], v[58:61]
	v_mfma_f32_16x16x32_bf16 v[46:49], v[146:149], v[206:209], v[46:49]
	v_mfma_f32_16x16x32_bf16 v[46:49], v[150:153], v[210:213], v[46:49]
	v_mfma_f32_16x16x32_bf16 v[42:45], v[154:157], v[206:209], v[42:45]
	v_mfma_f32_16x16x32_bf16 v[42:45], v[168:171], v[210:213], v[42:45]
	v_mfma_f32_16x16x32_bf16 v[30:33], v[146:149], v[214:217], v[30:33]
	v_mfma_f32_16x16x32_bf16 v[30:33], v[150:153], v[218:221], v[30:33]
	v_mfma_f32_16x16x32_bf16 v[26:29], v[154:157], v[214:217], v[26:29]
	v_mfma_f32_16x16x32_bf16 v[26:29], v[168:171], v[218:221], v[26:29]
	v_mfma_f32_16x16x32_bf16 v[14:17], v[146:149], v[222:225], v[14:17]
	v_mfma_f32_16x16x32_bf16 v[14:17], v[150:153], v[226:229], v[14:17]
	v_mfma_f32_16x16x32_bf16 v[10:13], v[154:157], v[222:225], v[10:13]
	v_mfma_f32_16x16x32_bf16 v[10:13], v[168:171], v[226:229], v[10:13]
	s_setprio 0
	s_setprio 1
	v_mfma_f32_16x16x32_bf16 v[54:57], v[172:175], v[198:201], v[54:57]
	v_mfma_f32_16x16x32_bf16 v[54:57], v[180:183], v[202:205], v[54:57]
	v_mfma_f32_16x16x32_bf16 v[50:53], v[184:187], v[198:201], v[50:53]
	v_mfma_f32_16x16x32_bf16 v[50:53], v[188:191], v[202:205], v[50:53]
	v_mfma_f32_16x16x32_bf16 v[38:41], v[172:175], v[206:209], v[38:41]
	v_mfma_f32_16x16x32_bf16 v[38:41], v[180:183], v[210:213], v[38:41]
	v_mfma_f32_16x16x32_bf16 v[34:37], v[184:187], v[206:209], v[34:37]
	v_mfma_f32_16x16x32_bf16 v[34:37], v[188:191], v[210:213], v[34:37]
	v_mfma_f32_16x16x32_bf16 v[22:25], v[172:175], v[214:217], v[22:25]
	v_mfma_f32_16x16x32_bf16 v[22:25], v[180:183], v[218:221], v[22:25]
	v_mfma_f32_16x16x32_bf16 v[18:21], v[184:187], v[214:217], v[18:21]
	v_mfma_f32_16x16x32_bf16 v[18:21], v[188:191], v[218:221], v[18:21]
	v_mfma_f32_16x16x32_bf16 v[6:9], v[172:175], v[222:225], v[6:9]
	v_mfma_f32_16x16x32_bf16 v[6:9], v[180:183], v[226:229], v[6:9]
	v_mfma_f32_16x16x32_bf16 v[2:5], v[184:187], v[222:225], v[2:5]
	v_mfma_f32_16x16x32_bf16 v[2:5], v[188:191], v[226:229], v[2:5]
	s_setprio 0
	s_barrier
	s_add_i32 s59, 0, 0x18000
	v_add_u32_e32 v158, s59, v160
	s_add_i32 s64, 0, 0x1c000
	ds_read_b128 v[146:149], v158
	ds_read_b128 v[150:153], v158 offset:1024
	ds_read_b128 v[154:157], v158 offset:2048
	ds_read_b128 v[168:171], v158 offset:3072
	v_add_u32_e32 v158, s64, v160
	ds_read_b128 v[172:175], v158
	ds_read_b128 v[180:183], v158 offset:1024
	ds_read_b128 v[184:187], v158 offset:2048
	ds_read_b128 v[188:191], v158 offset:3072
	v_lshl_add_u64 v[158:159], s[78:79], 0, v[130:131]
	s_mov_b32 m0, s15
	s_nop 0
	global_load_lds_dwordx4 v[158:159], off
	v_lshl_add_u64 v[158:159], s[78:79], 0, v[134:135]
	s_mov_b32 m0, s27
	s_nop 0
	global_load_lds_dwordx4 v[158:159], off
	s_add_u32 s62, s78, 0x4000
	s_addc_u32 s63, s79, 0
	s_mov_b32 m0, s28
	v_lshl_add_u64 v[158:159], s[62:63], 0, v[130:131]
	ds_read_b128 v[198:201], v164 offset:32768
	ds_read_b128 v[202:205], v164 offset:33792
	ds_read_b128 v[206:209], v164 offset:34816
	ds_read_b128 v[210:213], v164 offset:35840
	ds_read_b128 v[214:217], v164 offset:36864
	ds_read_b128 v[218:221], v164 offset:37888
	ds_read_b128 v[222:225], v164 offset:38912
	ds_read_b128 v[226:229], v164 offset:39936
	global_load_lds_dwordx4 v[158:159], off
	v_lshl_add_u64 v[158:159], s[62:63], 0, v[134:135]
	s_mov_b32 m0, s29
	s_nop 0
	global_load_lds_dwordx4 v[158:159], off
	s_waitcnt vmcnt(8)
	s_waitcnt lgkmcnt(0)
	s_barrier
; #define PG8_STAGE(bufoff, gbase, voff) do { _Pragma("unroll") for (int _i = 0; _i < 2; ++_i) \
;         __builtin_amdgcn_global_load_lds((const unsigned*)((const char*)(gbase) + (voff)[_i]), (PG8_LAS unsigned*)(lds + (bufoff) + ldsw + _i * 8192), 16, 0, 0); } while (0)
; #define PG8_LDA(dst, b, h) do { _Pragma("unroll") for (int m = 0; m < 4; ++m) _Pragma("unroll") for (int k = 0; k < 2; ++k) dst[m][k] = *(const PG8_LAS bf16x8*)(lds + PG8_SA(b, h) + aoff + m * 2048 + k * 1024); } while (0)
; #define PG8_MMA(ai, bj, At, Bt) do { __builtin_amdgcn_s_setprio(1); _Pragma("unroll") for (int m = 0; m < 4; ++m) _Pragma("unroll") for (int n = 0; n < 2; ++n) _Pragma("unroll") for (int k = 0; k < 2; ++k) \
;         acc[ai][bj][m][n] = __builtin_amdgcn_mfma_f32_16x16x32_bf16(Bt[n][k], At[m][k], acc[ai][bj][m][n], 0, 0, 0); __builtin_amdgcn_s_setprio(0); } while (0)
; #define PG8_WAIT_V(n) asm volatile("s_waitcnt vmcnt(" #n ")" ::: "memory")
; #define PG8_WAIT_L(n) asm volatile("s_waitcnt lgkmcnt(" #n ")" ::: "memory")
; #define PG8_BAR __builtin_amdgcn_s_barrier()
; #define PG8_SCHED __builtin_amdgcn_sched_barrier(0)
; template <class Epi, class Sched, bool ALIGN_EPI = false, bool SP2 = false>
; __device__ __forceinline__ void gemm_phase(PG8_LAS unsigned char* lds, const Gemm g, const Sched& S, const Epi& E) {
;     ...
;             PG8_WAIT_V(8); PG8_WAIT_L(0); PG8_BAR; PG8_MMA(0, 0, At, B0); PG8_MMA(0, 1, At, B1); PG8_BAR; PG8_SCHED;
;             PG8_LDA(At, 1, 1); PG8_STAGE(PG8_SB(1, 0), b3, voffB); PG8_STAGE(PG8_SB(1, 1), b3 + hstep, voffB); PG8_STAGE(PG8_SA(1, 0), a3, voffA);
;             PG8_WAIT_V(8); PG8_WAIT_L(0); PG8_BAR; PG8_MMA(1, 0, At, B0); PG8_MMA(1, 1, At, B1); PG8_BAR; PG8_SCHED;
	s_setprio 1
	s_waitcnt lgkmcnt(0)
	v_mfma_f32_16x16x32_bf16 v[126:129], v[146:149], v[198:201], v[126:129]
	v_mfma_f32_16x16x32_bf16 v[126:129], v[150:153], v[202:205], v[126:129]
	v_mfma_f32_16x16x32_bf16 v[122:125], v[154:157], v[198:201], v[122:125]
	v_mfma_f32_16x16x32_bf16 v[122:125], v[168:171], v[202:205], v[122:125]
	v_mfma_f32_16x16x32_bf16 v[110:113], v[146:149], v[206:209], v[110:113]
	v_mfma_f32_16x16x32_bf16 v[110:113], v[150:153], v[210:213], v[110:113]
	v_mfma_f32_16x16x32_bf16 v[106:109], v[154:157], v[206:209], v[106:109]
	v_mfma_f32_16x16x32_bf16 v[106:109], v[168:171], v[210:213], v[106:109]
	v_mfma_f32_16x16x32_bf16 v[94:97], v[146:149], v[214:217], v[94:97]
	v_mfma_f32_16x16x32_bf16 v[94:97], v[150:153], v[218:221], v[94:97]
	v_mfma_f32_16x16x32_bf16 v[90:93], v[154:157], v[214:217], v[90:93]
	v_mfma_f32_16x16x32_bf16 v[90:93], v[168:171], v[218:221], v[90:93]
	v_mfma_f32_16x16x32_bf16 v[78:81], v[146:149], v[222:225], v[78:81]
	v_mfma_f32_16x16x32_bf16 v[78:81], v[150:153], v[226:229], v[78:81]
	v_mfma_f32_16x16x32_bf16 v[74:77], v[154:157], v[222:225], v[74:77]
	v_mfma_f32_16x16x32_bf16 v[74:77], v[168:171], v[226:229], v[74:77]
	s_setprio 0
	s_setprio 1
	v_mfma_f32_16x16x32_bf16 v[118:121], v[172:175], v[198:201], v[118:121]
	v_mfma_f32_16x16x32_bf16 v[118:121], v[180:183], v[202:205], v[118:121]
	v_mfma_f32_16x16x32_bf16 v[114:117], v[184:187], v[198:201], v[114:117]
	v_mfma_f32_16x16x32_bf16 v[114:117], v[188:191], v[202:205], v[114:117]
	v_mfma_f32_16x16x32_bf16 v[102:105], v[172:175], v[206:209], v[102:105]
	v_mfma_f32_16x16x32_bf16 v[102:105], v[180:183], v[210:213], v[102:105]
	v_mfma_f32_16x16x32_bf16 v[98:101], v[184:187], v[206:209], v[98:101]
	v_mfma_f32_16x16x32_bf16 v[98:101], v[188:191], v[210:213], v[98:101]
	v_mfma_f32_16x16x32_bf16 v[86:89], v[172:175], v[214:217], v[86:89]
	v_mfma_f32_16x16x32_bf16 v[86:89], v[180:183], v[218:221], v[86:89]
	v_mfma_f32_16x16x32_bf16 v[82:85], v[184:187], v[214:217], v[82:85]
	v_mfma_f32_16x16x32_bf16 v[82:85], v[188:191], v[218:221], v[82:85]
	v_mfma_f32_16x16x32_bf16 v[70:73], v[172:175], v[222:225], v[70:73]
	v_mfma_f32_16x16x32_bf16 v[70:73], v[180:183], v[226:229], v[70:73]
	v_mfma_f32_16x16x32_bf16 v[66:69], v[184:187], v[222:225], v[66:69]
	v_mfma_f32_16x16x32_bf16 v[66:69], v[188:191], v[226:229], v[66:69]
	s_setprio 0
	s_barrier
	s_add_u32 s62, s76, 0x8000
	s_addc_u32 s63, s77, 0
	s_add_i32 s59, s59, s3
	v_lshl_add_u64 v[158:159], s[62:63], 0, v[132:133]
	s_mov_b32 m0, s59
	ds_read_b128 v[198:201], v164 offset:49152
	ds_read_b128 v[202:205], v164 offset:50176
	ds_read_b128 v[206:209], v164 offset:51200
	ds_read_b128 v[210:213], v164 offset:52224
	ds_read_b128 v[214:217], v164 offset:53248
	ds_read_b128 v[218:221], v164 offset:54272
	ds_read_b128 v[222:225], v164 offset:55296
	ds_read_b128 v[226:229], v164 offset:56320
	global_load_lds_dwordx4 v[158:159], off
	s_add_i32 m0, s59, 0x2000
	v_lshl_add_u64 v[158:159], s[62:63], 0, v[136:137]
	s_add_u32 s62, s76, 0xc000
	s_addc_u32 s63, s77, 0
	s_add_i32 s59, s64, s3
	global_load_lds_dwordx4 v[158:159], off
	v_lshl_add_u64 v[158:159], s[62:63], 0, v[132:133]
	s_mov_b32 m0, s59
	s_nop 0
	global_load_lds_dwordx4 v[158:159], off
	v_lshl_add_u64 v[158:159], s[62:63], 0, v[136:137]
	s_add_i32 m0, s59, 0x2000
	s_nop 0
	global_load_lds_dwordx4 v[158:159], off
	s_waitcnt vmcnt(6)
	s_waitcnt lgkmcnt(0)
	s_barrier
	s_setprio 1
	s_waitcnt lgkmcnt(0)
	v_mfma_f32_16x16x32_bf16 v[62:65], v[146:149], v[198:201], v[62:65]
	v_mfma_f32_16x16x32_bf16 v[62:65], v[150:153], v[202:205], v[62:65]
	v_mfma_f32_16x16x32_bf16 v[58:61], v[154:157], v[198:201], v[58:61]
	v_mfma_f32_16x16x32_bf16 v[58:61], v[168:171], v[202:205], v[58:61]
	v_mfma_f32_16x16x32_bf16 v[46:49], v[146:149], v[206:209], v[46:49]
	v_mfma_f32_16x16x32_bf16 v[46:49], v[150:153], v[210:213], v[46:49]
	v_mfma_f32_16x16x32_bf16 v[42:45], v[154:157], v[206:209], v[42:45]
	v_mfma_f32_16x16x32_bf16 v[42:45], v[168:171], v[210:213], v[42:45]
	v_mfma_f32_16x16x32_bf16 v[30:33], v[146:149], v[214:217], v[30:33]
	v_mfma_f32_16x16x32_bf16 v[30:33], v[150:153], v[218:221], v[30:33]
	v_mfma_f32_16x16x32_bf16 v[26:29], v[154:157], v[214:217], v[26:29]
	v_mfma_f32_16x16x32_bf16 v[26:29], v[168:171], v[218:221], v[26:29]
	v_mfma_f32_16x16x32_bf16 v[14:17], v[146:149], v[222:225], v[14:17]
	v_mfma_f32_16x16x32_bf16 v[14:17], v[150:153], v[226:229], v[14:17]
	v_mfma_f32_16x16x32_bf16 v[10:13], v[154:157], v[222:225], v[10:13]
	v_mfma_f32_16x16x32_bf16 v[10:13], v[168:171], v[226:229], v[10:13]
	s_setprio 0
	s_setprio 1
	v_mfma_f32_16x16x32_bf16 v[54:57], v[172:175], v[198:201], v[54:57]
	v_mfma_f32_16x16x32_bf16 v[54:57], v[180:183], v[202:205], v[54:57]
	v_mfma_f32_16x16x32_bf16 v[50:53], v[184:187], v[198:201], v[50:53]
	v_mfma_f32_16x16x32_bf16 v[50:53], v[188:191], v[202:205], v[50:53]
	v_mfma_f32_16x16x32_bf16 v[38:41], v[172:175], v[206:209], v[38:41]
	v_mfma_f32_16x16x32_bf16 v[38:41], v[180:183], v[210:213], v[38:41]
	v_mfma_f32_16x16x32_bf16 v[34:37], v[184:187], v[206:209], v[34:37]
	v_mfma_f32_16x16x32_bf16 v[34:37], v[188:191], v[210:213], v[34:37]
	v_mfma_f32_16x16x32_bf16 v[22:25], v[172:175], v[214:217], v[22:25]
	v_mfma_f32_16x16x32_bf16 v[22:25], v[180:183], v[218:221], v[22:25]
	v_mfma_f32_16x16x32_bf16 v[18:21], v[184:187], v[214:217], v[18:21]
	v_mfma_f32_16x16x32_bf16 v[18:21], v[188:191], v[218:221], v[18:21]
	v_mfma_f32_16x16x32_bf16 v[6:9], v[172:175], v[222:225], v[6:9]
	v_mfma_f32_16x16x32_bf16 v[6:9], v[180:183], v[226:229], v[6:9]
	v_mfma_f32_16x16x32_bf16 v[2:5], v[184:187], v[222:225], v[2:5]
	v_mfma_f32_16x16x32_bf16 v[2:5], v[188:191], v[226:229], v[2:5]
	s_setprio 0
	s_barrier
	s_add_i32 s58, s58, 2
	s_add_u32 s72, s72, 0x10000
	s_addc_u32 s73, s73, 0
	s_add_u32 s33, s33, 0x10000
	s_addc_u32 s56, s56, 0
	s_cmp_gt_u32 s58, 61
	s_cbranch_scc0 .LBB0_290
	s_and_b64 vcc, exec, s[12:13]
	s_cbranch_vccz .LBB0_293
	s_barrier

; #define PG8_STAGE(bufoff, gbase, voff) do { _Pragma("unroll") for (int _i = 0; _i < 2; ++_i) \
;         __builtin_amdgcn_global_load_lds((const unsigned*)((const char*)(gbase) + (voff)[_i]), (PG8_LAS unsigned*)(lds + (bufoff) + ldsw + _i * 8192), 16, 0, 0); } while (0)
; #define PG8_LDA(dst, b, h) do { _Pragma("unroll") for (int m = 0; m < 4; ++m) _Pragma("unroll") for (int k = 0; k < 2; ++k) dst[m][k] = *(const PG8_LAS bf16x8*)(lds + PG8_SA(b, h) + aoff + m * 2048 + k * 1024); } while (0)
; #define PG8_LDB(dst, b, h) do { _Pragma("unroll") for (int n = 0; n < 2; ++n) _Pragma("unroll") for (int k = 0; k < 2; ++k) dst[n][k] = *(const PG8_LAS bf16x8*)(lds + PG8_SB(b, h) + boff + n * 2048 + k * 1024); } while (0)
; #define PG8_MMA(ai, bj, At, Bt) do { __builtin_amdgcn_s_setprio(1); _Pragma("unroll") for (int m = 0; m < 4; ++m) _Pragma("unroll") for (int n = 0; n < 2; ++n) _Pragma("unroll") for (int k = 0; k < 2; ++k) \
;         acc[ai][bj][m][n] = __builtin_amdgcn_mfma_f32_16x16x32_bf16(Bt[n][k], At[m][k], acc[ai][bj][m][n], 0, 0, 0); __builtin_amdgcn_s_setprio(0); } while (0)
; #define PG8_WAIT_V(n) asm volatile("s_waitcnt vmcnt(" #n ")" ::: "memory")
; #define PG8_WAIT_L(n) asm volatile("s_waitcnt lgkmcnt(" #n ")" ::: "memory")
; #define PG8_BAR __builtin_amdgcn_s_barrier()
; #define PG8_SCHED __builtin_amdgcn_sched_barrier(0)
; template <class Epi, class Sched, bool ALIGN_EPI = false, bool SP2 = false>
; __device__ __forceinline__ void gemm_phase(PG8_LAS unsigned char* lds, const Gemm g, const Sched& S, const Epi& E) {
;     ...
;             PG8_LDB(B0, 0, 0); PG8_LDB(B1, 0, 1); PG8_SCHED; PG8_LDA(At, 0, 0); PG8_STAGE(PG8_SA(1, 1), a1 + hstep, voffA);
;             PG8_WAIT_V(8); PG8_WAIT_L(0); PG8_BAR; PG8_MMA(0, 0, At, B0); PG8_MMA(0, 1, At, B1); PG8_BAR; PG8_SCHED;
;             PG8_LDA(At, 0, 1); PG8_STAGE(PG8_SB(0, 0), b2, voffB); PG8_STAGE(PG8_SB(0, 1), b2 + hstep, voffB); PG8_STAGE(PG8_SA(0, 0), a2, voffA);
;             PG8_WAIT_V(8); PG8_WAIT_L(0); PG8_BAR; PG8_MMA(1, 0, At, B0); PG8_MMA(1, 1, At, B1); PG8_BAR; PG8_SCHED;
.LBB0_757:
	ds_read_b128 v[154:157], v149
	ds_read_b128 v[158:161], v149 offset:1024
	ds_read_b128 v[162:165], v149 offset:2048
	ds_read_b128 v[166:169], v149 offset:3072
	ds_read_b128 v[170:173], v150
	ds_read_b128 v[174:177], v150 offset:1024
	ds_read_b128 v[180:183], v150 offset:2048
	ds_read_b128 v[184:187], v150 offset:3072
	s_add_u32 s46, s44, 0x4000
	s_addc_u32 s47, s45, 0
	s_cmp_eq_u32 s70, 60
	s_cselect_b32 s50, s39, s46
	s_cselect_b32 s51, s17, s47
	s_cselect_b32 s48, s41, s68
	s_cselect_b32 s49, s15, s69
	s_add_u32 s46, s50, 0x8000
	s_addc_u32 s47, s51, 0
	s_sub_u32 s46, s44, 0x4000
	s_subb_u32 s47, s45, 0
	v_lshl_add_u64 v[146:147], s[46:47], 0, v[130:131]
	s_mov_b32 m0, s57
	s_nop 0
	global_load_lds_dwordx4 v[146:147], off
	v_lshl_add_u64 v[146:147], s[46:47], 0, v[134:135]
	s_mov_b32 m0, s58
	s_nop 0
	global_load_lds_dwordx4 v[146:147], off
	v_lshl_add_u64 v[146:147], s[44:45], 0, v[138:139]
	s_add_i32 m0, s26, 0xc000
	ds_read_b128 v[188:191], v151
	ds_read_b128 v[198:201], v151 offset:1024
	ds_read_b128 v[202:205], v151 offset:2048
	ds_read_b128 v[206:209], v151 offset:3072
	ds_read_b128 v[210:213], v151 offset:4096
	ds_read_b128 v[214:217], v151 offset:5120
	ds_read_b128 v[218:221], v151 offset:6144
	ds_read_b128 v[222:225], v151 offset:7168
	global_load_lds_dwordx4 v[146:147], off
	v_lshl_add_u64 v[146:147], s[44:45], 0, v[140:141]
	s_add_i32 m0, s26, 0xe000
	s_nop 0
	global_load_lds_dwordx4 v[146:147], off
	s_waitcnt vmcnt(8)
	s_waitcnt lgkmcnt(0)
	s_barrier
	s_setprio 1
	s_waitcnt lgkmcnt(0)
	v_mfma_f32_16x16x32_bf16 v[126:129], v[154:157], v[188:191], v[126:129]
	v_mfma_f32_16x16x32_bf16 v[126:129], v[158:161], v[198:201], v[126:129]
	v_mfma_f32_16x16x32_bf16 v[122:125], v[162:165], v[188:191], v[122:125]
	v_mfma_f32_16x16x32_bf16 v[122:125], v[166:169], v[198:201], v[122:125]
	v_mfma_f32_16x16x32_bf16 v[110:113], v[154:157], v[202:205], v[110:113]
	v_mfma_f32_16x16x32_bf16 v[110:113], v[158:161], v[206:209], v[110:113]
	v_mfma_f32_16x16x32_bf16 v[106:109], v[162:165], v[202:205], v[106:109]
	v_mfma_f32_16x16x32_bf16 v[106:109], v[166:169], v[206:209], v[106:109]
	v_mfma_f32_16x16x32_bf16 v[94:97], v[154:157], v[210:213], v[94:97]
	v_mfma_f32_16x16x32_bf16 v[94:97], v[158:161], v[214:217], v[94:97]
	v_mfma_f32_16x16x32_bf16 v[90:93], v[162:165], v[210:213], v[90:93]
	v_mfma_f32_16x16x32_bf16 v[90:93], v[166:169], v[214:217], v[90:93]
	v_mfma_f32_16x16x32_bf16 v[78:81], v[154:157], v[218:221], v[78:81]
	v_mfma_f32_16x16x32_bf16 v[78:81], v[158:161], v[222:225], v[78:81]
	v_mfma_f32_16x16x32_bf16 v[74:77], v[162:165], v[218:221], v[74:77]
	v_mfma_f32_16x16x32_bf16 v[74:77], v[166:169], v[222:225], v[74:77]
	s_setprio 0
	s_setprio 1
	v_mfma_f32_16x16x32_bf16 v[118:121], v[170:173], v[188:191], v[118:121]
	v_mfma_f32_16x16x32_bf16 v[118:121], v[174:177], v[198:201], v[118:121]
	v_mfma_f32_16x16x32_bf16 v[114:117], v[180:183], v[188:191], v[114:117]
	v_mfma_f32_16x16x32_bf16 v[114:117], v[184:187], v[198:201], v[114:117]
	v_mfma_f32_16x16x32_bf16 v[102:105], v[170:173], v[202:205], v[102:105]
	v_mfma_f32_16x16x32_bf16 v[102:105], v[174:177], v[206:209], v[102:105]
	v_mfma_f32_16x16x32_bf16 v[98:101], v[180:183], v[202:205], v[98:101]
	v_mfma_f32_16x16x32_bf16 v[98:101], v[184:187], v[206:209], v[98:101]
	v_mfma_f32_16x16x32_bf16 v[86:89], v[170:173], v[210:213], v[86:89]
	v_mfma_f32_16x16x32_bf16 v[86:89], v[174:177], v[214:217], v[86:89]
	v_mfma_f32_16x16x32_bf16 v[82:85], v[180:183], v[210:213], v[82:85]
	v_mfma_f32_16x16x32_bf16 v[82:85], v[184:187], v[214:217], v[82:85]
	v_mfma_f32_16x16x32_bf16 v[70:73], v[170:173], v[218:221], v[70:73]
	v_mfma_f32_16x16x32_bf16 v[70:73], v[174:177], v[222:225], v[70:73]
	v_mfma_f32_16x16x32_bf16 v[66:69], v[180:183], v[218:221], v[66:69]
	v_mfma_f32_16x16x32_bf16 v[66:69], v[184:187], v[222:225], v[66:69]
	s_setprio 0
	s_barrier
	s_add_i32 s71, s59, s3
	v_lshl_add_u64 v[146:147], s[48:49], 0, v[132:133]
	s_mov_b32 m0, s71
	ds_read_b128 v[188:191], v151 offset:16384
	ds_read_b128 v[198:201], v151 offset:17408
	ds_read_b128 v[202:205], v151 offset:18432
	ds_read_b128 v[206:209], v151 offset:19456
	ds_read_b128 v[210:213], v151 offset:20480
	ds_read_b128 v[214:217], v151 offset:21504
	ds_read_b128 v[218:221], v151 offset:22528
	ds_read_b128 v[222:225], v151 offset:23552
	global_load_lds_dwordx4 v[146:147], off
	s_add_i32 m0, s71, 0x2000
	s_add_u32 s72, s48, 0x4000
	v_lshl_add_u64 v[146:147], s[48:49], 0, v[136:137]
	s_addc_u32 s73, s49, 0
	s_add_i32 s71, s61, s3
	global_load_lds_dwordx4 v[146:147], off
	v_lshl_add_u64 v[146:147], s[72:73], 0, v[132:133]
	s_mov_b32 m0, s71
	s_nop 0
	global_load_lds_dwordx4 v[146:147], off
	v_lshl_add_u64 v[146:147], s[72:73], 0, v[136:137]
	s_add_i32 m0, s71, 0x2000
	s_nop 0
	global_load_lds_dwordx4 v[146:147], off
	s_waitcnt vmcnt(6)
	s_waitcnt lgkmcnt(0)
	s_barrier
; #define PG8_STAGE(bufoff, gbase, voff) do { _Pragma("unroll") for (int _i = 0; _i < 2; ++_i) \
;         __builtin_amdgcn_global_load_lds((const unsigned*)((const char*)(gbase) + (voff)[_i]), (PG8_LAS unsigned*)(lds + (bufoff) + ldsw + _i * 8192), 16, 0, 0); } while (0)
; #define PG8_LDA(dst, b, h) do { _Pragma("unroll") for (int m = 0; m < 4; ++m) _Pragma("unroll") for (int k = 0; k < 2; ++k) dst[m][k] = *(const PG8_LAS bf16x8*)(lds + PG8_SA(b, h) + aoff + m * 2048 + k * 1024); } while (0)
; #define PG8_LDB(dst, b, h) do { _Pragma("unroll") for (int n = 0; n < 2; ++n) _Pragma("unroll") for (int k = 0; k < 2; ++k) dst[n][k] = *(const PG8_LAS bf16x8*)(lds + PG8_SB(b, h) + boff + n * 2048 + k * 1024); } while (0)
; #define PG8_MMA(ai, bj, At, Bt) do { __builtin_amdgcn_s_setprio(1); _Pragma("unroll") for (int m = 0; m < 4; ++m) _Pragma("unroll") for (int n = 0; n < 2; ++n) _Pragma("unroll") for (int k = 0; k < 2; ++k) \
;         acc[ai][bj][m][n] = __builtin_amdgcn_mfma_f32_16x16x32_bf16(Bt[n][k], At[m][k], acc[ai][bj][m][n], 0, 0, 0); __builtin_amdgcn_s_setprio(0); } while (0)
; #define PG8_BAR __builtin_amdgcn_s_barrier()
; template <class Epi, class Sched, bool ALIGN_EPI = false, bool SP2 = false>
; __device__ __forceinline__ void gemm_phase(PG8_LAS unsigned char* lds, const Gemm g, const Sched& S, const Epi& E) {
;     ...
;             if constexpr (SP2) {
;             PG8_LDB(B0, 0, 0); PG8_LDB(B1, 0, 1); PG8_SCHED; PG8_LDA(At, 0, 0); PG8_STAGE(PG8_SA(1, 1), a1 + hstep, voffA);
;             PG8_WAIT_V(8); PG8_WAIT_L(0); PG8_BAR; PG8_MMA(0, 0, At, B0); PG8_MMA(0, 1, At, B1); PG8_BAR; PG8_SCHED;
;             PG8_LDA(At, 0, 1); PG8_STAGE(PG8_SB(0, 0), b2, voffB); PG8_STAGE(PG8_SB(0, 1), b2 + hstep, voffB); PG8_STAGE(PG8_SA(0, 0), a2, voffA);
;             PG8_WAIT_V(8); PG8_WAIT_L(0); PG8_BAR; PG8_MMA(1, 0, At, B0); PG8_MMA(1, 1, At, B1); PG8_BAR; PG8_SCHED;
;             PG8_LDB(B0, 1, 0); PG8_LDB(B1, 1, 1); PG8_SCHED; PG8_LDA(At, 1, 0); PG8_STAGE(PG8_SA(0, 1), a2 + hstep, voffA);
;             PG8_WAIT_V(8); PG8_WAIT_L(0); PG8_BAR; PG8_MMA(0, 0, At, B0); PG8_MMA(0, 1, At, B1); PG8_BAR; PG8_SCHED;
;             PG8_LDA(At, 1, 1); PG8_STAGE(PG8_SB(1, 0), b3, voffB); PG8_STAGE(PG8_SB(1, 1), b3 + hstep, voffB); PG8_STAGE(PG8_SA(1, 0), a3, voffA);
;             PG8_WAIT_V(8); PG8_WAIT_L(0); PG8_BAR; PG8_MMA(1, 0, At, B0); PG8_MMA(1, 1, At, B1); PG8_BAR; PG8_SCHED;
	s_setprio 1
	s_waitcnt lgkmcnt(0)
	v_mfma_f32_16x16x32_bf16 v[62:65], v[154:157], v[188:191], v[62:65]
	v_mfma_f32_16x16x32_bf16 v[62:65], v[158:161], v[198:201], v[62:65]
	v_mfma_f32_16x16x32_bf16 v[58:61], v[162:165], v[188:191], v[58:61]
	v_mfma_f32_16x16x32_bf16 v[58:61], v[166:169], v[198:201], v[58:61]
	v_mfma_f32_16x16x32_bf16 v[46:49], v[154:157], v[202:205], v[46:49]
	v_mfma_f32_16x16x32_bf16 v[46:49], v[158:161], v[206:209], v[46:49]
	v_mfma_f32_16x16x32_bf16 v[42:45], v[162:165], v[202:205], v[42:45]
	v_mfma_f32_16x16x32_bf16 v[42:45], v[166:169], v[206:209], v[42:45]
	v_mfma_f32_16x16x32_bf16 v[30:33], v[154:157], v[210:213], v[30:33]
	v_mfma_f32_16x16x32_bf16 v[30:33], v[158:161], v[214:217], v[30:33]
	v_mfma_f32_16x16x32_bf16 v[26:29], v[162:165], v[210:213], v[26:29]
	v_mfma_f32_16x16x32_bf16 v[26:29], v[166:169], v[214:217], v[26:29]
	v_mfma_f32_16x16x32_bf16 v[14:17], v[154:157], v[218:221], v[14:17]
	v_mfma_f32_16x16x32_bf16 v[14:17], v[158:161], v[222:225], v[14:17]
	v_mfma_f32_16x16x32_bf16 v[10:13], v[162:165], v[218:221], v[10:13]
	v_mfma_f32_16x16x32_bf16 v[10:13], v[166:169], v[222:225], v[10:13]
	s_setprio 0
	s_setprio 1
	v_mfma_f32_16x16x32_bf16 v[54:57], v[170:173], v[188:191], v[54:57]
	v_mfma_f32_16x16x32_bf16 v[54:57], v[174:177], v[198:201], v[54:57]
	v_mfma_f32_16x16x32_bf16 v[50:53], v[180:183], v[188:191], v[50:53]
	v_mfma_f32_16x16x32_bf16 v[50:53], v[184:187], v[198:201], v[50:53]
	v_mfma_f32_16x16x32_bf16 v[38:41], v[170:173], v[202:205], v[38:41]
	v_mfma_f32_16x16x32_bf16 v[38:41], v[174:177], v[206:209], v[38:41]
	v_mfma_f32_16x16x32_bf16 v[34:37], v[180:183], v[202:205], v[34:37]
	v_mfma_f32_16x16x32_bf16 v[34:37], v[184:187], v[206:209], v[34:37]
	v_mfma_f32_16x16x32_bf16 v[22:25], v[170:173], v[210:213], v[22:25]
	v_mfma_f32_16x16x32_bf16 v[22:25], v[174:177], v[214:217], v[22:25]
	v_mfma_f32_16x16x32_bf16 v[18:21], v[180:183], v[210:213], v[18:21]
	v_mfma_f32_16x16x32_bf16 v[18:21], v[184:187], v[214:217], v[18:21]
	v_mfma_f32_16x16x32_bf16 v[6:9], v[170:173], v[218:221], v[6:9]
	v_mfma_f32_16x16x32_bf16 v[6:9], v[174:177], v[222:225], v[6:9]
	v_mfma_f32_16x16x32_bf16 v[2:5], v[180:183], v[218:221], v[2:5]
	v_mfma_f32_16x16x32_bf16 v[2:5], v[184:187], v[222:225], v[2:5]
	s_setprio 0
	s_barrier
	s_add_i32 s71, 0, 0x18000
	v_add_u32_e32 v146, s71, v1
	s_add_i32 s72, 0, 0x1c000
	ds_read_b128 v[154:157], v146
	ds_read_b128 v[158:161], v146 offset:1024
	ds_read_b128 v[162:165], v146 offset:2048
	ds_read_b128 v[166:169], v146 offset:3072
	v_add_u32_e32 v146, s72, v1
	ds_read_b128 v[170:173], v146
	ds_read_b128 v[174:177], v146 offset:1024
	ds_read_b128 v[180:183], v146 offset:2048
	ds_read_b128 v[184:187], v146 offset:3072
	v_lshl_add_u64 v[146:147], s[50:51], 0, v[130:131]
	s_mov_b32 m0, s26
	s_nop 0
	global_load_lds_dwordx4 v[146:147], off
	v_lshl_add_u64 v[146:147], s[50:51], 0, v[134:135]
	s_mov_b32 m0, s27
	s_nop 0
	global_load_lds_dwordx4 v[146:147], off
	s_add_u32 s50, s50, 0x4000
	s_addc_u32 s51, s51, 0
	s_mov_b32 m0, s28
	v_lshl_add_u64 v[146:147], s[50:51], 0, v[130:131]
	ds_read_b128 v[188:191], v151 offset:32768
	ds_read_b128 v[198:201], v151 offset:33792
	ds_read_b128 v[202:205], v151 offset:34816
	ds_read_b128 v[206:209], v151 offset:35840
	ds_read_b128 v[210:213], v151 offset:36864
	ds_read_b128 v[214:217], v151 offset:37888
	ds_read_b128 v[218:221], v151 offset:38912
	ds_read_b128 v[222:225], v151 offset:39936
	global_load_lds_dwordx4 v[146:147], off
	v_lshl_add_u64 v[146:147], s[50:51], 0, v[134:135]
	s_mov_b32 m0, s29
	s_nop 0
	global_load_lds_dwordx4 v[146:147], off
	s_waitcnt vmcnt(8)
	s_waitcnt lgkmcnt(0)
	s_barrier
; #define PG8_STAGE(bufoff, gbase, voff) do { _Pragma("unroll") for (int _i = 0; _i < 2; ++_i) \
;         __builtin_amdgcn_global_load_lds((const unsigned*)((const char*)(gbase) + (voff)[_i]), (PG8_LAS unsigned*)(lds + (bufoff) + ldsw + _i * 8192), 16, 0, 0); } while (0)
; #define PG8_LDA(dst, b, h) do { _Pragma("unroll") for (int m = 0; m < 4; ++m) _Pragma("unroll") for (int k = 0; k < 2; ++k) dst[m][k] = *(const PG8_LAS bf16x8*)(lds + PG8_SA(b, h) + aoff + m * 2048 + k * 1024); } while (0)
; #define PG8_LDB(dst, b, h) do { _Pragma("unroll") for (int n = 0; n < 2; ++n) _Pragma("unroll") for (int k = 0; k < 2; ++k) dst[n][k] = *(const PG8_LAS bf16x8*)(lds + PG8_SB(b, h) + boff + n * 2048 + k * 1024); } while (0)
; #define PG8_MMA(ai, bj, At, Bt) do { __builtin_amdgcn_s_setprio(1); _Pragma("unroll") for (int m = 0; m < 4; ++m) _Pragma("unroll") for (int n = 0; n < 2; ++n) _Pragma("unroll") for (int k = 0; k < 2; ++k) \
;         acc[ai][bj][m][n] = __builtin_amdgcn_mfma_f32_16x16x32_bf16(Bt[n][k], At[m][k], acc[ai][bj][m][n], 0, 0, 0); __builtin_amdgcn_s_setprio(0); } while (0)
; #define PG8_BAR __builtin_amdgcn_s_barrier()
; template <class Epi, class Sched, bool ALIGN_EPI = false, bool SP2 = false>
; __device__ __forceinline__ void gemm_phase(PG8_LAS unsigned char* lds, const Gemm g, const Sched& S, const Epi& E) {
;     ...
;             if constexpr (SP2) {
;             PG8_LDB(B0, 0, 0); PG8_LDB(B1, 0, 1); PG8_SCHED; PG8_LDA(At, 0, 0); PG8_STAGE(PG8_SA(1, 1), a1 + hstep, voffA);
;             PG8_WAIT_V(8); PG8_WAIT_L(0); PG8_BAR; PG8_MMA(0, 0, At, B0); PG8_MMA(0, 1, At, B1); PG8_BAR; PG8_SCHED;
;             PG8_LDA(At, 0, 1); PG8_STAGE(PG8_SB(0, 0), b2, voffB); PG8_STAGE(PG8_SB(0, 1), b2 + hstep, voffB); PG8_STAGE(PG8_SA(0, 0), a2, voffA);
;             PG8_WAIT_V(8); PG8_WAIT_L(0); PG8_BAR; PG8_MMA(1, 0, At, B0); PG8_MMA(1, 1, At, B1); PG8_BAR; PG8_SCHED;
;             PG8_LDB(B0, 1, 0); PG8_LDB(B1, 1, 1); PG8_SCHED; PG8_LDA(At, 1, 0); PG8_STAGE(PG8_SA(0, 1), a2 + hstep, voffA);
;             PG8_WAIT_V(8); PG8_WAIT_L(0); PG8_BAR; PG8_MMA(0, 0, At, B0); PG8_MMA(0, 1, At, B1); PG8_BAR; PG8_SCHED;
;             PG8_LDA(At, 1, 1); PG8_STAGE(PG8_SB(1, 0), b3, voffB); PG8_STAGE(PG8_SB(1, 1), b3 + hstep, voffB); PG8_STAGE(PG8_SA(1, 0), a3, voffA);
;             PG8_WAIT_V(8); PG8_WAIT_L(0); PG8_BAR; PG8_MMA(1, 0, At, B0); PG8_MMA(1, 1, At, B1); PG8_BAR; PG8_SCHED;
	s_setprio 1
	s_waitcnt lgkmcnt(0)
	v_mfma_f32_16x16x32_bf16 v[126:129], v[154:157], v[188:191], v[126:129]
	v_mfma_f32_16x16x32_bf16 v[126:129], v[158:161], v[198:201], v[126:129]
	v_mfma_f32_16x16x32_bf16 v[122:125], v[162:165], v[188:191], v[122:125]
	v_mfma_f32_16x16x32_bf16 v[122:125], v[166:169], v[198:201], v[122:125]
	v_mfma_f32_16x16x32_bf16 v[110:113], v[154:157], v[202:205], v[110:113]
	v_mfma_f32_16x16x32_bf16 v[110:113], v[158:161], v[206:209], v[110:113]
	v_mfma_f32_16x16x32_bf16 v[106:109], v[162:165], v[202:205], v[106:109]
	v_mfma_f32_16x16x32_bf16 v[106:109], v[166:169], v[206:209], v[106:109]
	v_mfma_f32_16x16x32_bf16 v[94:97], v[154:157], v[210:213], v[94:97]
	v_mfma_f32_16x16x32_bf16 v[94:97], v[158:161], v[214:217], v[94:97]
	v_mfma_f32_16x16x32_bf16 v[90:93], v[162:165], v[210:213], v[90:93]
	v_mfma_f32_16x16x32_bf16 v[90:93], v[166:169], v[214:217], v[90:93]
	v_mfma_f32_16x16x32_bf16 v[78:81], v[154:157], v[218:221], v[78:81]
	v_mfma_f32_16x16x32_bf16 v[78:81], v[158:161], v[222:225], v[78:81]
	v_mfma_f32_16x16x32_bf16 v[74:77], v[162:165], v[218:221], v[74:77]
	v_mfma_f32_16x16x32_bf16 v[74:77], v[166:169], v[222:225], v[74:77]
	s_setprio 0
	s_setprio 1
	v_mfma_f32_16x16x32_bf16 v[118:121], v[170:173], v[188:191], v[118:121]
	v_mfma_f32_16x16x32_bf16 v[118:121], v[174:177], v[198:201], v[118:121]
	v_mfma_f32_16x16x32_bf16 v[114:117], v[180:183], v[188:191], v[114:117]
	v_mfma_f32_16x16x32_bf16 v[114:117], v[184:187], v[198:201], v[114:117]
	v_mfma_f32_16x16x32_bf16 v[102:105], v[170:173], v[202:205], v[102:105]
	v_mfma_f32_16x16x32_bf16 v[102:105], v[174:177], v[206:209], v[102:105]
	v_mfma_f32_16x16x32_bf16 v[98:101], v[180:183], v[202:205], v[98:101]
	v_mfma_f32_16x16x32_bf16 v[98:101], v[184:187], v[206:209], v[98:101]
	v_mfma_f32_16x16x32_bf16 v[86:89], v[170:173], v[210:213], v[86:89]
	v_mfma_f32_16x16x32_bf16 v[86:89], v[174:177], v[214:217], v[86:89]
	v_mfma_f32_16x16x32_bf16 v[82:85], v[180:183], v[210:213], v[82:85]
	v_mfma_f32_16x16x32_bf16 v[82:85], v[184:187], v[214:217], v[82:85]
	v_mfma_f32_16x16x32_bf16 v[70:73], v[170:173], v[218:221], v[70:73]
	v_mfma_f32_16x16x32_bf16 v[70:73], v[174:177], v[222:225], v[70:73]
	v_mfma_f32_16x16x32_bf16 v[66:69], v[180:183], v[218:221], v[66:69]
	v_mfma_f32_16x16x32_bf16 v[66:69], v[184:187], v[222:225], v[66:69]
	s_setprio 0
	s_barrier
	s_add_u32 s50, s48, 0x8000
	s_addc_u32 s51, s49, 0
	s_add_i32 s71, s71, s3
	v_lshl_add_u64 v[146:147], s[50:51], 0, v[132:133]
	s_mov_b32 m0, s71
	ds_read_b128 v[188:191], v151 offset:49152
	ds_read_b128 v[198:201], v151 offset:50176
	ds_read_b128 v[202:205], v151 offset:51200
	ds_read_b128 v[206:209], v151 offset:52224
	ds_read_b128 v[210:213], v151 offset:53248
	ds_read_b128 v[214:217], v151 offset:54272
	ds_read_b128 v[218:221], v151 offset:55296
	ds_read_b128 v[222:225], v151 offset:56320
	global_load_lds_dwordx4 v[146:147], off
	s_add_i32 m0, s71, 0x2000
	s_add_u32 s48, s48, 0xc000
	v_lshl_add_u64 v[146:147], s[50:51], 0, v[136:137]
	s_addc_u32 s49, s49, 0
	s_add_i32 s50, s72, s3
	global_load_lds_dwordx4 v[146:147], off
	v_lshl_add_u64 v[146:147], s[48:49], 0, v[132:133]
	s_mov_b32 m0, s50
	s_nop 0
	global_load_lds_dwordx4 v[146:147], off
	v_lshl_add_u64 v[146:147], s[48:49], 0, v[136:137]
	s_add_i32 m0, s50, 0x2000
	s_nop 0
	global_load_lds_dwordx4 v[146:147], off
	s_waitcnt vmcnt(6)
	s_waitcnt lgkmcnt(0)
	s_barrier
	s_setprio 1
	s_waitcnt lgkmcnt(0)
	v_mfma_f32_16x16x32_bf16 v[62:65], v[154:157], v[188:191], v[62:65]
	v_mfma_f32_16x16x32_bf16 v[62:65], v[158:161], v[198:201], v[62:65]
	v_mfma_f32_16x16x32_bf16 v[58:61], v[162:165], v[188:191], v[58:61]
	v_mfma_f32_16x16x32_bf16 v[58:61], v[166:169], v[198:201], v[58:61]
	v_mfma_f32_16x16x32_bf16 v[46:49], v[154:157], v[202:205], v[46:49]
	v_mfma_f32_16x16x32_bf16 v[46:49], v[158:161], v[206:209], v[46:49]
	v_mfma_f32_16x16x32_bf16 v[42:45], v[162:165], v[202:205], v[42:45]
	v_mfma_f32_16x16x32_bf16 v[42:45], v[166:169], v[206:209], v[42:45]
	v_mfma_f32_16x16x32_bf16 v[30:33], v[154:157], v[210:213], v[30:33]
	v_mfma_f32_16x16x32_bf16 v[30:33], v[158:161], v[214:217], v[30:33]
	v_mfma_f32_16x16x32_bf16 v[26:29], v[162:165], v[210:213], v[26:29]
	v_mfma_f32_16x16x32_bf16 v[26:29], v[166:169], v[214:217], v[26:29]
	v_mfma_f32_16x16x32_bf16 v[14:17], v[154:157], v[218:221], v[14:17]
	v_mfma_f32_16x16x32_bf16 v[14:17], v[158:161], v[222:225], v[14:17]
	v_mfma_f32_16x16x32_bf16 v[10:13], v[162:165], v[218:221], v[10:13]
	v_mfma_f32_16x16x32_bf16 v[10:13], v[166:169], v[222:225], v[10:13]
	s_setprio 0
	s_setprio 1
	v_mfma_f32_16x16x32_bf16 v[54:57], v[170:173], v[188:191], v[54:57]
	v_mfma_f32_16x16x32_bf16 v[54:57], v[174:177], v[198:201], v[54:57]
	v_mfma_f32_16x16x32_bf16 v[50:53], v[180:183], v[188:191], v[50:53]
	v_mfma_f32_16x16x32_bf16 v[50:53], v[184:187], v[198:201], v[50:53]
	v_mfma_f32_16x16x32_bf16 v[38:41], v[170:173], v[202:205], v[38:41]
	v_mfma_f32_16x16x32_bf16 v[38:41], v[174:177], v[206:209], v[38:41]
	v_mfma_f32_16x16x32_bf16 v[34:37], v[180:183], v[202:205], v[34:37]
	v_mfma_f32_16x16x32_bf16 v[34:37], v[184:187], v[206:209], v[34:37]
	v_mfma_f32_16x16x32_bf16 v[22:25], v[170:173], v[210:213], v[22:25]
	v_mfma_f32_16x16x32_bf16 v[22:25], v[174:177], v[214:217], v[22:25]
	v_mfma_f32_16x16x32_bf16 v[18:21], v[180:183], v[210:213], v[18:21]
	v_mfma_f32_16x16x32_bf16 v[18:21], v[184:187], v[214:217], v[18:21]
	v_mfma_f32_16x16x32_bf16 v[6:9], v[170:173], v[218:221], v[6:9]
	v_mfma_f32_16x16x32_bf16 v[6:9], v[174:177], v[222:225], v[6:9]
	v_mfma_f32_16x16x32_bf16 v[2:5], v[180:183], v[218:221], v[2:5]
	v_mfma_f32_16x16x32_bf16 v[2:5], v[184:187], v[222:225], v[2:5]
	s_setprio 0
	s_barrier
	s_add_i32 s70, s70, 2
	s_add_u32 s44, s44, 0x10000
	s_addc_u32 s45, s45, 0
	s_add_u32 s68, s68, 0x10000
	s_addc_u32 s69, s69, 0
	s_cmp_gt_u32 s70, 61
	s_cbranch_scc0 .LBB0_757
	s_and_b64 vcc, exec, s[12:13]
	s_cbranch_vccz .LBB0_760
	s_barrier

; #define PG8_STAGE(bufoff, gbase, voff) do { _Pragma("unroll") for (int _i = 0; _i < 2; ++_i) \
;         __builtin_amdgcn_global_load_lds((const unsigned*)((const char*)(gbase) + (voff)[_i]), (PG8_LAS unsigned*)(lds + (bufoff) + ldsw + _i * 8192), 16, 0, 0); } while (0)
; #define PG8_LDA(dst, b, h) do { _Pragma("unroll") for (int m = 0; m < 4; ++m) _Pragma("unroll") for (int k = 0; k < 2; ++k) dst[m][k] = *(const PG8_LAS bf16x8*)(lds + PG8_SA(b, h) + aoff + m * 2048 + k * 1024); } while (0)
; #define PG8_LDB(dst, b, h) do { _Pragma("unroll") for (int n = 0; n < 2; ++n) _Pragma("unroll") for (int k = 0; k < 2; ++k) dst[n][k] = *(const PG8_LAS bf16x8*)(lds + PG8_SB(b, h) + boff + n * 2048 + k * 1024); } while (0)
; #define PG8_WAIT_V(n) asm volatile("s_waitcnt vmcnt(" #n ")" ::: "memory")
; template <class Epi, class Sched, bool ALIGN_EPI = false, bool SP2 = false>
; __device__ __forceinline__ void gemm_phase(PG8_LAS unsigned char* lds, const Gemm g, const Sched& S, const Epi& E) {
;     ...
;             const char* a1 = cA + (size_t)(t + 1) * kstep;
;             const char* a2 = last ? nA : cA + (size_t)(t + 2) * kstep; const char* b2 = last ? nB : cB + (size_t)(t + 2) * kstep;
;             const char* a3 = a2 + kstep; const char* b3 = b2 + kstep;
;             if (last && has_next) S.a_ready(nxt);
;             if constexpr (SP2) {
;             PG8_LDB(B0, 0, 0); PG8_LDB(B1, 0, 1); PG8_SCHED; PG8_LDA(At, 0, 0); PG8_STAGE(PG8_SA(1, 1), a1 + hstep, voffA);
;             PG8_WAIT_V(8); PG8_WAIT_L(0); PG8_BAR; PG8_MMA(0, 0, At, B0); PG8_MMA(0, 1, At, B1); PG8_BAR; PG8_SCHED;
;             PG8_LDA(At, 0, 1); PG8_STAGE(PG8_SB(0, 0), b2, voffB); PG8_STAGE(PG8_SB(0, 1), b2 + hstep, voffB); PG8_STAGE(PG8_SA(0, 0), a2, voffA);
;             PG8_WAIT_V(8); PG8_WAIT_L(0); PG8_BAR; PG8_MMA(1, 0, At, B0); PG8_MMA(1, 1, At, B1); PG8_BAR; PG8_SCHED;
;             PG8_LDB(B0, 1, 0); PG8_LDB(B1, 1, 1); PG8_SCHED; PG8_LDA(At, 1, 0); PG8_STAGE(PG8_SA(0, 1), a2 + hstep, voffA);
;             PG8_WAIT_V(8); PG8_WAIT_L(0); PG8_BAR; PG8_MMA(0, 0, At, B0); PG8_MMA(0, 1, At, B1); PG8_BAR; PG8_SCHED;
;             PG8_LDA(At, 1, 1); PG8_STAGE(PG8_SB(1, 0), b3, voffB); PG8_STAGE(PG8_SB(1, 1), b3 + hstep, voffB); PG8_STAGE(PG8_SA(1, 0), a3, voffA);
;             PG8_WAIT_V(8); PG8_WAIT_L(0); PG8_BAR; PG8_MMA(1, 0, At, B0); PG8_MMA(1, 1, At, B1); PG8_BAR; PG8_SCHED;
.LBB0_840:
	ds_read_b128 v[148:151], v153
	ds_read_b128 v[158:161], v153 offset:1024
	ds_read_b128 v[162:165], v153 offset:2048
	ds_read_b128 v[166:169], v153 offset:3072
	ds_read_b128 v[170:173], v154
	ds_read_b128 v[174:177], v154 offset:1024
	ds_read_b128 v[180:183], v154 offset:2048
	ds_read_b128 v[184:187], v154 offset:3072
	s_add_u32 s42, s40, 0x4000
	s_addc_u32 s43, s41, 0
	s_cmp_eq_u32 s69, 60
	s_cselect_b32 s46, s65, s42
	s_cselect_b32 s47, s23, s43
	s_cselect_b32 s44, s66, s67
	s_cselect_b32 s45, s17, s68
	s_add_u32 s42, s46, 0x8000
	s_addc_u32 s43, s47, 0
	s_sub_u32 s42, s40, 0x4000
	s_subb_u32 s43, s41, 0
	v_lshl_add_u64 v[226:227], s[42:43], 0, v[130:131]
	s_mov_b32 m0, s50
	s_nop 0
	global_load_lds_dwordx4 v[226:227], off
	v_lshl_add_u64 v[226:227], s[42:43], 0, v[134:135]
	s_mov_b32 m0, s51
	s_nop 0
	global_load_lds_dwordx4 v[226:227], off
	v_lshl_add_u64 v[226:227], s[40:41], 0, v[140:141]
	s_add_i32 m0, s28, 0xc000
	ds_read_b128 v[188:191], v155
	ds_read_b128 v[198:201], v155 offset:1024
	ds_read_b128 v[202:205], v155 offset:2048
	ds_read_b128 v[206:209], v155 offset:3072
	ds_read_b128 v[210:213], v155 offset:4096
	ds_read_b128 v[214:217], v155 offset:5120
	ds_read_b128 v[218:221], v155 offset:6144
	ds_read_b128 v[222:225], v155 offset:7168
	global_load_lds_dwordx4 v[226:227], off
	v_lshl_add_u64 v[226:227], s[40:41], 0, v[142:143]
	s_add_i32 m0, s28, 0xe000
	s_nop 0
	global_load_lds_dwordx4 v[226:227], off
	s_waitcnt vmcnt(8)
	s_waitcnt lgkmcnt(0)
	s_barrier
	s_setprio 1
	s_waitcnt lgkmcnt(0)
	v_mfma_f32_16x16x32_bf16 v[126:129], v[148:151], v[188:191], v[126:129]
	v_mfma_f32_16x16x32_bf16 v[126:129], v[158:161], v[198:201], v[126:129]
	v_mfma_f32_16x16x32_bf16 v[122:125], v[162:165], v[188:191], v[122:125]
	v_mfma_f32_16x16x32_bf16 v[122:125], v[166:169], v[198:201], v[122:125]
	v_mfma_f32_16x16x32_bf16 v[110:113], v[148:151], v[202:205], v[110:113]
	v_mfma_f32_16x16x32_bf16 v[110:113], v[158:161], v[206:209], v[110:113]
	v_mfma_f32_16x16x32_bf16 v[106:109], v[162:165], v[202:205], v[106:109]
	v_mfma_f32_16x16x32_bf16 v[106:109], v[166:169], v[206:209], v[106:109]
	v_mfma_f32_16x16x32_bf16 v[94:97], v[148:151], v[210:213], v[94:97]
	v_mfma_f32_16x16x32_bf16 v[94:97], v[158:161], v[214:217], v[94:97]
	v_mfma_f32_16x16x32_bf16 v[90:93], v[162:165], v[210:213], v[90:93]
	v_mfma_f32_16x16x32_bf16 v[90:93], v[166:169], v[214:217], v[90:93]
	v_mfma_f32_16x16x32_bf16 v[78:81], v[148:151], v[218:221], v[78:81]
	v_mfma_f32_16x16x32_bf16 v[78:81], v[158:161], v[222:225], v[78:81]
	v_mfma_f32_16x16x32_bf16 v[74:77], v[162:165], v[218:221], v[74:77]
	v_mfma_f32_16x16x32_bf16 v[74:77], v[166:169], v[222:225], v[74:77]
	s_setprio 0
	s_setprio 1
	v_mfma_f32_16x16x32_bf16 v[118:121], v[170:173], v[188:191], v[118:121]
	v_mfma_f32_16x16x32_bf16 v[118:121], v[174:177], v[198:201], v[118:121]
	v_mfma_f32_16x16x32_bf16 v[114:117], v[180:183], v[188:191], v[114:117]
	v_mfma_f32_16x16x32_bf16 v[114:117], v[184:187], v[198:201], v[114:117]
	v_mfma_f32_16x16x32_bf16 v[102:105], v[170:173], v[202:205], v[102:105]
	v_mfma_f32_16x16x32_bf16 v[102:105], v[174:177], v[206:209], v[102:105]
	v_mfma_f32_16x16x32_bf16 v[98:101], v[180:183], v[202:205], v[98:101]
	v_mfma_f32_16x16x32_bf16 v[98:101], v[184:187], v[206:209], v[98:101]
	v_mfma_f32_16x16x32_bf16 v[86:89], v[170:173], v[210:213], v[86:89]
	v_mfma_f32_16x16x32_bf16 v[86:89], v[174:177], v[214:217], v[86:89]
	v_mfma_f32_16x16x32_bf16 v[82:85], v[180:183], v[210:213], v[82:85]
	v_mfma_f32_16x16x32_bf16 v[82:85], v[184:187], v[214:217], v[82:85]
	v_mfma_f32_16x16x32_bf16 v[70:73], v[170:173], v[218:221], v[70:73]
	v_mfma_f32_16x16x32_bf16 v[70:73], v[174:177], v[222:225], v[70:73]
	v_mfma_f32_16x16x32_bf16 v[66:69], v[180:183], v[218:221], v[66:69]
	v_mfma_f32_16x16x32_bf16 v[66:69], v[184:187], v[222:225], v[66:69]
	s_setprio 0
	s_barrier
	s_add_i32 s70, s56, s3
	v_lshl_add_u64 v[226:227], s[44:45], 0, v[132:133]
	s_mov_b32 m0, s70
	ds_read_b128 v[188:191], v155 offset:16384
	ds_read_b128 v[198:201], v155 offset:17408
	ds_read_b128 v[202:205], v155 offset:18432
	ds_read_b128 v[206:209], v155 offset:19456
	ds_read_b128 v[210:213], v155 offset:20480
	ds_read_b128 v[214:217], v155 offset:21504
	ds_read_b128 v[218:221], v155 offset:22528
	ds_read_b128 v[222:225], v155 offset:23552
	global_load_lds_dwordx4 v[226:227], off
	s_add_i32 m0, s70, 0x2000
	s_add_u32 s70, s44, 0x4000
	v_lshl_add_u64 v[226:227], s[44:45], 0, v[136:137]
	s_addc_u32 s71, s45, 0
	s_add_i32 s72, s57, s3
	global_load_lds_dwordx4 v[226:227], off
	v_lshl_add_u64 v[226:227], s[70:71], 0, v[132:133]
	s_mov_b32 m0, s72
	s_nop 0
	global_load_lds_dwordx4 v[226:227], off
	v_lshl_add_u64 v[226:227], s[70:71], 0, v[136:137]
	s_add_i32 m0, s72, 0x2000
	s_nop 0
	global_load_lds_dwordx4 v[226:227], off
	s_waitcnt vmcnt(6)
	s_waitcnt lgkmcnt(0)
	s_barrier
; #define PG8_STAGE(bufoff, gbase, voff) do { _Pragma("unroll") for (int _i = 0; _i < 2; ++_i) \
;         __builtin_amdgcn_global_load_lds((const unsigned*)((const char*)(gbase) + (voff)[_i]), (PG8_LAS unsigned*)(lds + (bufoff) + ldsw + _i * 8192), 16, 0, 0); } while (0)
; #define PG8_LDA(dst, b, h) do { _Pragma("unroll") for (int m = 0; m < 4; ++m) _Pragma("unroll") for (int k = 0; k < 2; ++k) dst[m][k] = *(const PG8_LAS bf16x8*)(lds + PG8_SA(b, h) + aoff + m * 2048 + k * 1024); } while (0)
; #define PG8_LDB(dst, b, h) do { _Pragma("unroll") for (int n = 0; n < 2; ++n) _Pragma("unroll") for (int k = 0; k < 2; ++k) dst[n][k] = *(const PG8_LAS bf16x8*)(lds + PG8_SB(b, h) + boff + n * 2048 + k * 1024); } while (0)
; #define PG8_MMA(ai, bj, At, Bt) do { __builtin_amdgcn_s_setprio(1); _Pragma("unroll") for (int m = 0; m < 4; ++m) _Pragma("unroll") for (int n = 0; n < 2; ++n) _Pragma("unroll") for (int k = 0; k < 2; ++k) \
;         acc[ai][bj][m][n] = __builtin_amdgcn_mfma_f32_16x16x32_bf16(Bt[n][k], At[m][k], acc[ai][bj][m][n], 0, 0, 0); __builtin_amdgcn_s_setprio(0); } while (0)
; #define PG8_BAR __builtin_amdgcn_s_barrier()
; template <class Epi, class Sched, bool ALIGN_EPI = false, bool SP2 = false>
; __device__ __forceinline__ void gemm_phase(PG8_LAS unsigned char* lds, const Gemm g, const Sched& S, const Epi& E) {
;     ...
;             if constexpr (SP2) {
;             PG8_LDB(B0, 0, 0); PG8_LDB(B1, 0, 1); PG8_SCHED; PG8_LDA(At, 0, 0); PG8_STAGE(PG8_SA(1, 1), a1 + hstep, voffA);
;             PG8_WAIT_V(8); PG8_WAIT_L(0); PG8_BAR; PG8_MMA(0, 0, At, B0); PG8_MMA(0, 1, At, B1); PG8_BAR; PG8_SCHED;
;             PG8_LDA(At, 0, 1); PG8_STAGE(PG8_SB(0, 0), b2, voffB); PG8_STAGE(PG8_SB(0, 1), b2 + hstep, voffB); PG8_STAGE(PG8_SA(0, 0), a2, voffA);
;             PG8_WAIT_V(8); PG8_WAIT_L(0); PG8_BAR; PG8_MMA(1, 0, At, B0); PG8_MMA(1, 1, At, B1); PG8_BAR; PG8_SCHED;
;             PG8_LDB(B0, 1, 0); PG8_LDB(B1, 1, 1); PG8_SCHED; PG8_LDA(At, 1, 0); PG8_STAGE(PG8_SA(0, 1), a2 + hstep, voffA);
;             PG8_WAIT_V(8); PG8_WAIT_L(0); PG8_BAR; PG8_MMA(0, 0, At, B0); PG8_MMA(0, 1, At, B1); PG8_BAR; PG8_SCHED;
;             PG8_LDA(At, 1, 1); PG8_STAGE(PG8_SB(1, 0), b3, voffB); PG8_STAGE(PG8_SB(1, 1), b3 + hstep, voffB); PG8_STAGE(PG8_SA(1, 0), a3, voffA);
;             PG8_WAIT_V(8); PG8_WAIT_L(0); PG8_BAR; PG8_MMA(1, 0, At, B0); PG8_MMA(1, 1, At, B1); PG8_BAR; PG8_SCHED;
	s_setprio 1
	s_waitcnt lgkmcnt(0)
	v_mfma_f32_16x16x32_bf16 v[62:65], v[148:151], v[188:191], v[62:65]
	v_mfma_f32_16x16x32_bf16 v[62:65], v[158:161], v[198:201], v[62:65]
	v_mfma_f32_16x16x32_bf16 v[58:61], v[162:165], v[188:191], v[58:61]
	v_mfma_f32_16x16x32_bf16 v[58:61], v[166:169], v[198:201], v[58:61]
	v_mfma_f32_16x16x32_bf16 v[46:49], v[148:151], v[202:205], v[46:49]
	v_mfma_f32_16x16x32_bf16 v[46:49], v[158:161], v[206:209], v[46:49]
	v_mfma_f32_16x16x32_bf16 v[42:45], v[162:165], v[202:205], v[42:45]
	v_mfma_f32_16x16x32_bf16 v[42:45], v[166:169], v[206:209], v[42:45]
	v_mfma_f32_16x16x32_bf16 v[30:33], v[148:151], v[210:213], v[30:33]
	v_mfma_f32_16x16x32_bf16 v[30:33], v[158:161], v[214:217], v[30:33]
	v_mfma_f32_16x16x32_bf16 v[26:29], v[162:165], v[210:213], v[26:29]
	v_mfma_f32_16x16x32_bf16 v[26:29], v[166:169], v[214:217], v[26:29]
	v_mfma_f32_16x16x32_bf16 v[14:17], v[148:151], v[218:221], v[14:17]
	v_mfma_f32_16x16x32_bf16 v[14:17], v[158:161], v[222:225], v[14:17]
	v_mfma_f32_16x16x32_bf16 v[10:13], v[162:165], v[218:221], v[10:13]
	v_mfma_f32_16x16x32_bf16 v[10:13], v[166:169], v[222:225], v[10:13]
	s_setprio 0
	s_setprio 1
	v_mfma_f32_16x16x32_bf16 v[54:57], v[170:173], v[188:191], v[54:57]
	v_mfma_f32_16x16x32_bf16 v[54:57], v[174:177], v[198:201], v[54:57]
	v_mfma_f32_16x16x32_bf16 v[50:53], v[180:183], v[188:191], v[50:53]
	v_mfma_f32_16x16x32_bf16 v[50:53], v[184:187], v[198:201], v[50:53]
	v_mfma_f32_16x16x32_bf16 v[38:41], v[170:173], v[202:205], v[38:41]
	v_mfma_f32_16x16x32_bf16 v[38:41], v[174:177], v[206:209], v[38:41]
	v_mfma_f32_16x16x32_bf16 v[34:37], v[180:183], v[202:205], v[34:37]
	v_mfma_f32_16x16x32_bf16 v[34:37], v[184:187], v[206:209], v[34:37]
	v_mfma_f32_16x16x32_bf16 v[22:25], v[170:173], v[210:213], v[22:25]
	v_mfma_f32_16x16x32_bf16 v[22:25], v[174:177], v[214:217], v[22:25]
	v_mfma_f32_16x16x32_bf16 v[18:21], v[180:183], v[210:213], v[18:21]
	v_mfma_f32_16x16x32_bf16 v[18:21], v[184:187], v[214:217], v[18:21]
	v_mfma_f32_16x16x32_bf16 v[6:9], v[170:173], v[218:221], v[6:9]
	v_mfma_f32_16x16x32_bf16 v[6:9], v[174:177], v[222:225], v[6:9]
	v_mfma_f32_16x16x32_bf16 v[2:5], v[180:183], v[218:221], v[2:5]
	v_mfma_f32_16x16x32_bf16 v[2:5], v[184:187], v[222:225], v[2:5]
	s_setprio 0
	s_barrier
	s_add_i32 s70, 0, 0x18000
	v_add_u32_e32 v138, s70, v1
	s_add_i32 s71, 0, 0x1c000
	ds_read_b128 v[148:151], v138
	ds_read_b128 v[158:161], v138 offset:1024
	ds_read_b128 v[162:165], v138 offset:2048
	ds_read_b128 v[166:169], v138 offset:3072
	v_add_u32_e32 v138, s71, v1
	ds_read_b128 v[170:173], v138
	ds_read_b128 v[174:177], v138 offset:1024
	ds_read_b128 v[180:183], v138 offset:2048
	ds_read_b128 v[184:187], v138 offset:3072
	v_lshl_add_u64 v[226:227], s[46:47], 0, v[130:131]
	s_mov_b32 m0, s28
	s_nop 0
	global_load_lds_dwordx4 v[226:227], off
	v_lshl_add_u64 v[226:227], s[46:47], 0, v[134:135]
	s_mov_b32 m0, s29
	s_nop 0
	global_load_lds_dwordx4 v[226:227], off
	s_add_u32 s46, s46, 0x4000
	s_addc_u32 s47, s47, 0
	s_mov_b32 m0, s30
	v_lshl_add_u64 v[226:227], s[46:47], 0, v[130:131]
	ds_read_b128 v[188:191], v155 offset:32768
	ds_read_b128 v[198:201], v155 offset:33792
	ds_read_b128 v[202:205], v155 offset:34816
	ds_read_b128 v[206:209], v155 offset:35840
	ds_read_b128 v[210:213], v155 offset:36864
	ds_read_b128 v[214:217], v155 offset:37888
	ds_read_b128 v[218:221], v155 offset:38912
	ds_read_b128 v[222:225], v155 offset:39936
	global_load_lds_dwordx4 v[226:227], off
	v_lshl_add_u64 v[226:227], s[46:47], 0, v[134:135]
	s_mov_b32 m0, s31
	s_nop 0
	global_load_lds_dwordx4 v[226:227], off
	s_waitcnt vmcnt(8)
	s_waitcnt lgkmcnt(0)
	s_barrier
; #define PG8_STAGE(bufoff, gbase, voff) do { _Pragma("unroll") for (int _i = 0; _i < 2; ++_i) \
;         __builtin_amdgcn_global_load_lds((const unsigned*)((const char*)(gbase) + (voff)[_i]), (PG8_LAS unsigned*)(lds + (bufoff) + ldsw + _i * 8192), 16, 0, 0); } while (0)
; #define PG8_LDA(dst, b, h) do { _Pragma("unroll") for (int m = 0; m < 4; ++m) _Pragma("unroll") for (int k = 0; k < 2; ++k) dst[m][k] = *(const PG8_LAS bf16x8*)(lds + PG8_SA(b, h) + aoff + m * 2048 + k * 1024); } while (0)
; #define PG8_LDB(dst, b, h) do { _Pragma("unroll") for (int n = 0; n < 2; ++n) _Pragma("unroll") for (int k = 0; k < 2; ++k) dst[n][k] = *(const PG8_LAS bf16x8*)(lds + PG8_SB(b, h) + boff + n * 2048 + k * 1024); } while (0)
; #define PG8_MMA(ai, bj, At, Bt) do { __builtin_amdgcn_s_setprio(1); _Pragma("unroll") for (int m = 0; m < 4; ++m) _Pragma("unroll") for (int n = 0; n < 2; ++n) _Pragma("unroll") for (int k = 0; k < 2; ++k) \
;         acc[ai][bj][m][n] = __builtin_amdgcn_mfma_f32_16x16x32_bf16(Bt[n][k], At[m][k], acc[ai][bj][m][n], 0, 0, 0); __builtin_amdgcn_s_setprio(0); } while (0)
; #define PG8_BAR __builtin_amdgcn_s_barrier()
; template <class Epi, class Sched, bool ALIGN_EPI = false, bool SP2 = false>
; __device__ __forceinline__ void gemm_phase(PG8_LAS unsigned char* lds, const Gemm g, const Sched& S, const Epi& E) {
;     ...
;             if constexpr (SP2) {
;             PG8_LDB(B0, 0, 0); PG8_LDB(B1, 0, 1); PG8_SCHED; PG8_LDA(At, 0, 0); PG8_STAGE(PG8_SA(1, 1), a1 + hstep, voffA);
;             PG8_WAIT_V(8); PG8_WAIT_L(0); PG8_BAR; PG8_MMA(0, 0, At, B0); PG8_MMA(0, 1, At, B1); PG8_BAR; PG8_SCHED;
;             PG8_LDA(At, 0, 1); PG8_STAGE(PG8_SB(0, 0), b2, voffB); PG8_STAGE(PG8_SB(0, 1), b2 + hstep, voffB); PG8_STAGE(PG8_SA(0, 0), a2, voffA);
;             PG8_WAIT_V(8); PG8_WAIT_L(0); PG8_BAR; PG8_MMA(1, 0, At, B0); PG8_MMA(1, 1, At, B1); PG8_BAR; PG8_SCHED;
;             PG8_LDB(B0, 1, 0); PG8_LDB(B1, 1, 1); PG8_SCHED; PG8_LDA(At, 1, 0); PG8_STAGE(PG8_SA(0, 1), a2 + hstep, voffA);
;             PG8_WAIT_V(8); PG8_WAIT_L(0); PG8_BAR; PG8_MMA(0, 0, At, B0); PG8_MMA(0, 1, At, B1); PG8_BAR; PG8_SCHED;
;             PG8_LDA(At, 1, 1); PG8_STAGE(PG8_SB(1, 0), b3, voffB); PG8_STAGE(PG8_SB(1, 1), b3 + hstep, voffB); PG8_STAGE(PG8_SA(1, 0), a3, voffA);
;             PG8_WAIT_V(8); PG8_WAIT_L(0); PG8_BAR; PG8_MMA(1, 0, At, B0); PG8_MMA(1, 1, At, B1); PG8_BAR; PG8_SCHED;
	s_setprio 1
	s_waitcnt lgkmcnt(0)
	v_mfma_f32_16x16x32_bf16 v[126:129], v[148:151], v[188:191], v[126:129]
	v_mfma_f32_16x16x32_bf16 v[126:129], v[158:161], v[198:201], v[126:129]
	v_mfma_f32_16x16x32_bf16 v[122:125], v[162:165], v[188:191], v[122:125]
	v_mfma_f32_16x16x32_bf16 v[122:125], v[166:169], v[198:201], v[122:125]
	v_mfma_f32_16x16x32_bf16 v[110:113], v[148:151], v[202:205], v[110:113]
	v_mfma_f32_16x16x32_bf16 v[110:113], v[158:161], v[206:209], v[110:113]
	v_mfma_f32_16x16x32_bf16 v[106:109], v[162:165], v[202:205], v[106:109]
	v_mfma_f32_16x16x32_bf16 v[106:109], v[166:169], v[206:209], v[106:109]
	v_mfma_f32_16x16x32_bf16 v[94:97], v[148:151], v[210:213], v[94:97]
	v_mfma_f32_16x16x32_bf16 v[94:97], v[158:161], v[214:217], v[94:97]
	v_mfma_f32_16x16x32_bf16 v[90:93], v[162:165], v[210:213], v[90:93]
	v_mfma_f32_16x16x32_bf16 v[90:93], v[166:169], v[214:217], v[90:93]
	v_mfma_f32_16x16x32_bf16 v[78:81], v[148:151], v[218:221], v[78:81]
	v_mfma_f32_16x16x32_bf16 v[78:81], v[158:161], v[222:225], v[78:81]
	v_mfma_f32_16x16x32_bf16 v[74:77], v[162:165], v[218:221], v[74:77]
	v_mfma_f32_16x16x32_bf16 v[74:77], v[166:169], v[222:225], v[74:77]
	s_setprio 0
	s_setprio 1
	v_mfma_f32_16x16x32_bf16 v[118:121], v[170:173], v[188:191], v[118:121]
	v_mfma_f32_16x16x32_bf16 v[118:121], v[174:177], v[198:201], v[118:121]
	v_mfma_f32_16x16x32_bf16 v[114:117], v[180:183], v[188:191], v[114:117]
	v_mfma_f32_16x16x32_bf16 v[114:117], v[184:187], v[198:201], v[114:117]
	v_mfma_f32_16x16x32_bf16 v[102:105], v[170:173], v[202:205], v[102:105]
	v_mfma_f32_16x16x32_bf16 v[102:105], v[174:177], v[206:209], v[102:105]
	v_mfma_f32_16x16x32_bf16 v[98:101], v[180:183], v[202:205], v[98:101]
	v_mfma_f32_16x16x32_bf16 v[98:101], v[184:187], v[206:209], v[98:101]
	v_mfma_f32_16x16x32_bf16 v[86:89], v[170:173], v[210:213], v[86:89]
	v_mfma_f32_16x16x32_bf16 v[86:89], v[174:177], v[214:217], v[86:89]
	v_mfma_f32_16x16x32_bf16 v[82:85], v[180:183], v[210:213], v[82:85]
	v_mfma_f32_16x16x32_bf16 v[82:85], v[184:187], v[214:217], v[82:85]
	v_mfma_f32_16x16x32_bf16 v[70:73], v[170:173], v[218:221], v[70:73]
	v_mfma_f32_16x16x32_bf16 v[70:73], v[174:177], v[222:225], v[70:73]
	v_mfma_f32_16x16x32_bf16 v[66:69], v[180:183], v[218:221], v[66:69]
	v_mfma_f32_16x16x32_bf16 v[66:69], v[184:187], v[222:225], v[66:69]
	s_setprio 0
	s_barrier
	s_add_u32 s46, s44, 0x8000
	s_addc_u32 s47, s45, 0
	s_add_i32 s70, s70, s3
	v_lshl_add_u64 v[226:227], s[46:47], 0, v[132:133]
	s_mov_b32 m0, s70
	ds_read_b128 v[188:191], v155 offset:49152
	ds_read_b128 v[198:201], v155 offset:50176
	ds_read_b128 v[202:205], v155 offset:51200
	ds_read_b128 v[206:209], v155 offset:52224
	ds_read_b128 v[210:213], v155 offset:53248
	ds_read_b128 v[214:217], v155 offset:54272
	ds_read_b128 v[218:221], v155 offset:55296
	ds_read_b128 v[222:225], v155 offset:56320
	global_load_lds_dwordx4 v[226:227], off
	s_add_i32 m0, s70, 0x2000
	s_add_u32 s44, s44, 0xc000
	v_lshl_add_u64 v[226:227], s[46:47], 0, v[136:137]
	s_addc_u32 s45, s45, 0
	s_add_i32 s46, s71, s3
	global_load_lds_dwordx4 v[226:227], off
	v_lshl_add_u64 v[226:227], s[44:45], 0, v[132:133]
	s_mov_b32 m0, s46
	s_nop 0
	global_load_lds_dwordx4 v[226:227], off
	v_lshl_add_u64 v[226:227], s[44:45], 0, v[136:137]
	s_add_i32 m0, s46, 0x2000
	s_nop 0
	global_load_lds_dwordx4 v[226:227], off
	s_waitcnt vmcnt(6)
	s_waitcnt lgkmcnt(0)
	s_barrier
	s_setprio 1
	s_waitcnt lgkmcnt(0)
	v_mfma_f32_16x16x32_bf16 v[62:65], v[148:151], v[188:191], v[62:65]
	v_mfma_f32_16x16x32_bf16 v[62:65], v[158:161], v[198:201], v[62:65]
	v_mfma_f32_16x16x32_bf16 v[58:61], v[162:165], v[188:191], v[58:61]
	v_mfma_f32_16x16x32_bf16 v[58:61], v[166:169], v[198:201], v[58:61]
	v_mfma_f32_16x16x32_bf16 v[46:49], v[148:151], v[202:205], v[46:49]
	v_mfma_f32_16x16x32_bf16 v[46:49], v[158:161], v[206:209], v[46:49]
	v_mfma_f32_16x16x32_bf16 v[42:45], v[162:165], v[202:205], v[42:45]
	v_mfma_f32_16x16x32_bf16 v[42:45], v[166:169], v[206:209], v[42:45]
	v_mfma_f32_16x16x32_bf16 v[30:33], v[148:151], v[210:213], v[30:33]
	v_mfma_f32_16x16x32_bf16 v[30:33], v[158:161], v[214:217], v[30:33]
	v_mfma_f32_16x16x32_bf16 v[26:29], v[162:165], v[210:213], v[26:29]
	v_mfma_f32_16x16x32_bf16 v[26:29], v[166:169], v[214:217], v[26:29]
	v_mfma_f32_16x16x32_bf16 v[14:17], v[148:151], v[218:221], v[14:17]
	v_mfma_f32_16x16x32_bf16 v[14:17], v[158:161], v[222:225], v[14:17]
	v_mfma_f32_16x16x32_bf16 v[10:13], v[162:165], v[218:221], v[10:13]
	v_mfma_f32_16x16x32_bf16 v[10:13], v[166:169], v[222:225], v[10:13]
	s_setprio 0
	s_setprio 1
	v_mfma_f32_16x16x32_bf16 v[54:57], v[170:173], v[188:191], v[54:57]
	v_mfma_f32_16x16x32_bf16 v[54:57], v[174:177], v[198:201], v[54:57]
	v_mfma_f32_16x16x32_bf16 v[50:53], v[180:183], v[188:191], v[50:53]
	v_mfma_f32_16x16x32_bf16 v[50:53], v[184:187], v[198:201], v[50:53]
	v_mfma_f32_16x16x32_bf16 v[38:41], v[170:173], v[202:205], v[38:41]
	v_mfma_f32_16x16x32_bf16 v[38:41], v[174:177], v[206:209], v[38:41]
	v_mfma_f32_16x16x32_bf16 v[34:37], v[180:183], v[202:205], v[34:37]
	v_mfma_f32_16x16x32_bf16 v[34:37], v[184:187], v[206:209], v[34:37]
	v_mfma_f32_16x16x32_bf16 v[22:25], v[170:173], v[210:213], v[22:25]
	v_mfma_f32_16x16x32_bf16 v[22:25], v[174:177], v[214:217], v[22:25]
	v_mfma_f32_16x16x32_bf16 v[18:21], v[180:183], v[210:213], v[18:21]
	v_mfma_f32_16x16x32_bf16 v[18:21], v[184:187], v[214:217], v[18:21]
	v_mfma_f32_16x16x32_bf16 v[6:9], v[170:173], v[218:221], v[6:9]
	v_mfma_f32_16x16x32_bf16 v[6:9], v[174:177], v[222:225], v[6:9]
	v_mfma_f32_16x16x32_bf16 v[2:5], v[180:183], v[218:221], v[2:5]
	v_mfma_f32_16x16x32_bf16 v[2:5], v[184:187], v[222:225], v[2:5]
	s_setprio 0
	s_barrier
	s_add_i32 s69, s69, 2
	s_add_u32 s40, s40, 0x10000
	s_addc_u32 s41, s41, 0
	s_add_u32 s67, s67, 0x10000
	s_addc_u32 s68, s68, 0
	s_cmp_gt_u32 s69, 61
	s_cbranch_scc0 .LBB0_840
	s_and_b64 vcc, exec, s[14:15]
	s_cbranch_vccz .LBB0_843
	s_barrier

; #define PG8_STAGE(bufoff, gbase, voff) do { _Pragma("unroll") for (int _i = 0; _i < 2; ++_i) \
;         __builtin_amdgcn_global_load_lds((const unsigned*)((const char*)(gbase) + (voff)[_i]), (PG8_LAS unsigned*)(lds + (bufoff) + ldsw + _i * 8192), 16, 0, 0); } while (0)
; #define PG8_LDA(dst, b, h) do { _Pragma("unroll") for (int m = 0; m < 4; ++m) _Pragma("unroll") for (int k = 0; k < 2; ++k) dst[m][k] = *(const PG8_LAS bf16x8*)(lds + PG8_SA(b, h) + aoff + m * 2048 + k * 1024); } while (0)
; #define PG8_LDB(dst, b, h) do { _Pragma("unroll") for (int n = 0; n < 2; ++n) _Pragma("unroll") for (int k = 0; k < 2; ++k) dst[n][k] = *(const PG8_LAS bf16x8*)(lds + PG8_SB(b, h) + boff + n * 2048 + k * 1024); } while (0)
; #define PG8_WAIT_V(n) asm volatile("s_waitcnt vmcnt(" #n ")" ::: "memory")
; template <class Epi, class Sched, bool ALIGN_EPI = false, bool SP2 = false>
; __device__ __forceinline__ void gemm_phase(PG8_LAS unsigned char* lds, const Gemm g, const Sched& S, const Epi& E) {
;     ...
;             const char* a1 = cA + (size_t)(t + 1) * kstep;
;             const char* a2 = last ? nA : cA + (size_t)(t + 2) * kstep; const char* b2 = last ? nB : cB + (size_t)(t + 2) * kstep;
;             const char* a3 = a2 + kstep; const char* b3 = b2 + kstep;
;             if (last && has_next) S.a_ready(nxt);
;             if constexpr (SP2) {
;             PG8_LDB(B0, 0, 0); PG8_LDB(B1, 0, 1); PG8_SCHED; PG8_LDA(At, 0, 0); PG8_STAGE(PG8_SA(1, 1), a1 + hstep, voffA);
;             PG8_WAIT_V(8); PG8_WAIT_L(0); PG8_BAR; PG8_MMA(0, 0, At, B0); PG8_MMA(0, 1, At, B1); PG8_BAR; PG8_SCHED;
;             PG8_LDA(At, 0, 1); PG8_STAGE(PG8_SB(0, 0), b2, voffB); PG8_STAGE(PG8_SB(0, 1), b2 + hstep, voffB); PG8_STAGE(PG8_SA(0, 0), a2, voffA);
;             PG8_WAIT_V(8); PG8_WAIT_L(0); PG8_BAR; PG8_MMA(1, 0, At, B0); PG8_MMA(1, 1, At, B1); PG8_BAR; PG8_SCHED;
;             PG8_LDB(B0, 1, 0); PG8_LDB(B1, 1, 1); PG8_SCHED; PG8_LDA(At, 1, 0); PG8_STAGE(PG8_SA(0, 1), a2 + hstep, voffA);
;             PG8_WAIT_V(8); PG8_WAIT_L(0); PG8_BAR; PG8_MMA(0, 0, At, B0); PG8_MMA(0, 1, At, B1); PG8_BAR; PG8_SCHED;
;             PG8_LDA(At, 1, 1); PG8_STAGE(PG8_SB(1, 0), b3, voffB); PG8_STAGE(PG8_SB(1, 1), b3 + hstep, voffB); PG8_STAGE(PG8_SA(1, 0), a3, voffA);
;             PG8_WAIT_V(8); PG8_WAIT_L(0); PG8_BAR; PG8_MMA(1, 0, At, B0); PG8_MMA(1, 1, At, B1); PG8_BAR; PG8_SCHED;
.LBB0_939:
	s_or_b32 s24, s59, 1
	s_lshl_b64 s[62:63], s[24:25], 15
	s_add_i32 s24, s59, 2
	ds_read_b128 v[156:159], v193
	ds_read_b128 v[160:163], v193 offset:1024
	ds_read_b128 v[196:199], v193 offset:2048
	ds_read_b128 v[200:203], v193 offset:3072
	ds_read_b128 v[204:207], v194
	ds_read_b128 v[208:211], v194 offset:1024
	ds_read_b128 v[212:215], v194 offset:2048
	ds_read_b128 v[216:219], v194 offset:3072
	s_lshl_b64 s[8:9], s[24:25], 15
	s_add_u32 s44, s6, s8
	s_addc_u32 s45, s7, s9
	s_cmpk_eq_i32 s59, 0xaa
	s_cselect_b32 s46, s58, s44
	s_cselect_b32 s47, s56, s45
	s_cselect_b32 s44, 0, s8
	s_cselect_b32 s45, 0, s9
	s_add_u32 s8, s46, 0x8000
	s_addc_u32 s9, s47, 0
	s_add_u32 s44, s14, s44
	s_addc_u32 s45, s15, s45
	s_add_u32 s62, s6, s62
	s_addc_u32 s63, s7, s63
	s_add_u32 s62, s62, 0x4000
	s_addc_u32 s63, s63, 0
	s_sub_u32 s8, s62, 0x4000
	s_subb_u32 s9, s63, 0
	v_lshl_add_u64 v[164:165], s[8:9], 0, v[130:131]
	s_mov_b32 m0, s51
	s_nop 0
	global_load_lds_dwordx4 v[164:165], off
	v_lshl_add_u64 v[164:165], s[8:9], 0, v[134:135]
	s_mov_b32 m0, s57
	s_nop 0
	global_load_lds_dwordx4 v[164:165], off
	v_lshl_add_u64 v[164:165], s[62:63], 0, v[130:131]
	s_add_i32 m0, s30, 0xc000
	ds_read_b128 v[220:223], v186
	ds_read_b128 v[224:227], v186 offset:1024
	ds_read_b128 v[228:231], v186 offset:2048
	ds_read_b128 v[232:235], v186 offset:3072
	ds_read_b128 v[236:239], v186 offset:4096
	ds_read_b128 v[240:243], v186 offset:5120
	ds_read_b128 v[244:247], v186 offset:6144
	ds_read_b128 v[248:251], v186 offset:7168
	global_load_lds_dwordx4 v[164:165], off
	v_lshl_add_u64 v[164:165], s[62:63], 0, v[134:135]
	s_add_i32 m0, s30, 0xe000
	s_nop 0
	global_load_lds_dwordx4 v[164:165], off
	s_waitcnt vmcnt(8)
	s_waitcnt lgkmcnt(0)
	s_barrier
	s_setprio 1
	s_waitcnt lgkmcnt(0)
	v_mfma_f32_16x16x32_bf16 v[126:129], v[156:159], v[220:223], v[126:129]
	v_mfma_f32_16x16x32_bf16 v[126:129], v[160:163], v[224:227], v[126:129]
	v_mfma_f32_16x16x32_bf16 v[122:125], v[196:199], v[220:223], v[122:125]
	v_mfma_f32_16x16x32_bf16 v[122:125], v[200:203], v[224:227], v[122:125]
	v_mfma_f32_16x16x32_bf16 v[110:113], v[156:159], v[228:231], v[110:113]
	v_mfma_f32_16x16x32_bf16 v[110:113], v[160:163], v[232:235], v[110:113]
	v_mfma_f32_16x16x32_bf16 v[106:109], v[196:199], v[228:231], v[106:109]
	v_mfma_f32_16x16x32_bf16 v[106:109], v[200:203], v[232:235], v[106:109]
	v_mfma_f32_16x16x32_bf16 v[94:97], v[156:159], v[236:239], v[94:97]
	v_mfma_f32_16x16x32_bf16 v[94:97], v[160:163], v[240:243], v[94:97]
	v_mfma_f32_16x16x32_bf16 v[90:93], v[196:199], v[236:239], v[90:93]
	v_mfma_f32_16x16x32_bf16 v[90:93], v[200:203], v[240:243], v[90:93]
	v_mfma_f32_16x16x32_bf16 v[78:81], v[156:159], v[244:247], v[78:81]
	v_mfma_f32_16x16x32_bf16 v[78:81], v[160:163], v[248:251], v[78:81]
	v_mfma_f32_16x16x32_bf16 v[74:77], v[196:199], v[244:247], v[74:77]
	v_mfma_f32_16x16x32_bf16 v[74:77], v[200:203], v[248:251], v[74:77]
	s_setprio 0
	s_setprio 1
	v_mfma_f32_16x16x32_bf16 v[118:121], v[204:207], v[220:223], v[118:121]
	v_mfma_f32_16x16x32_bf16 v[118:121], v[208:211], v[224:227], v[118:121]
	v_mfma_f32_16x16x32_bf16 v[114:117], v[212:215], v[220:223], v[114:117]
	v_mfma_f32_16x16x32_bf16 v[114:117], v[216:219], v[224:227], v[114:117]
	v_mfma_f32_16x16x32_bf16 v[102:105], v[204:207], v[228:231], v[102:105]
	v_mfma_f32_16x16x32_bf16 v[102:105], v[208:211], v[232:235], v[102:105]
	v_mfma_f32_16x16x32_bf16 v[98:101], v[212:215], v[228:231], v[98:101]
	v_mfma_f32_16x16x32_bf16 v[98:101], v[216:219], v[232:235], v[98:101]
	v_mfma_f32_16x16x32_bf16 v[86:89], v[204:207], v[236:239], v[86:89]
	v_mfma_f32_16x16x32_bf16 v[86:89], v[208:211], v[240:243], v[86:89]
	v_mfma_f32_16x16x32_bf16 v[82:85], v[212:215], v[236:239], v[82:85]
	v_mfma_f32_16x16x32_bf16 v[82:85], v[216:219], v[240:243], v[82:85]
	v_mfma_f32_16x16x32_bf16 v[70:73], v[204:207], v[244:247], v[70:73]
	v_mfma_f32_16x16x32_bf16 v[70:73], v[208:211], v[248:251], v[70:73]
	v_mfma_f32_16x16x32_bf16 v[66:69], v[212:215], v[244:247], v[66:69]
	v_mfma_f32_16x16x32_bf16 v[66:69], v[216:219], v[248:251], v[66:69]
	s_setprio 0
	s_barrier
	s_add_i32 s62, s67, s29
	v_lshl_add_u64 v[164:165], s[44:45], 0, v[132:133]
	s_mov_b32 m0, s62
	ds_read_b128 v[220:223], v186 offset:16384
	ds_read_b128 v[224:227], v186 offset:17408
	ds_read_b128 v[228:231], v186 offset:18432
	ds_read_b128 v[232:235], v186 offset:19456
	ds_read_b128 v[236:239], v186 offset:20480
	ds_read_b128 v[240:243], v186 offset:21504
	ds_read_b128 v[244:247], v186 offset:22528
	ds_read_b128 v[248:251], v186 offset:23552
	global_load_lds_dwordx4 v[164:165], off
	s_add_i32 m0, s62, 0x2000
	s_add_u32 s62, s44, 0x4000
	v_lshl_add_u64 v[164:165], s[44:45], 0, v[136:137]
	s_addc_u32 s63, s45, 0
	s_add_i32 s72, s68, s29
	global_load_lds_dwordx4 v[164:165], off
	v_lshl_add_u64 v[164:165], s[62:63], 0, v[132:133]
	s_mov_b32 m0, s72
	s_nop 0
	global_load_lds_dwordx4 v[164:165], off
	v_lshl_add_u64 v[164:165], s[62:63], 0, v[136:137]
	s_add_i32 m0, s72, 0x2000
	s_nop 0
	global_load_lds_dwordx4 v[164:165], off
	s_waitcnt vmcnt(6)
	s_waitcnt lgkmcnt(0)
	s_barrier
; #define PG8_STAGE(bufoff, gbase, voff) do { _Pragma("unroll") for (int _i = 0; _i < 2; ++_i) \
;         __builtin_amdgcn_global_load_lds((const unsigned*)((const char*)(gbase) + (voff)[_i]), (PG8_LAS unsigned*)(lds + (bufoff) + ldsw + _i * 8192), 16, 0, 0); } while (0)
; #define PG8_LDA(dst, b, h) do { _Pragma("unroll") for (int m = 0; m < 4; ++m) _Pragma("unroll") for (int k = 0; k < 2; ++k) dst[m][k] = *(const PG8_LAS bf16x8*)(lds + PG8_SA(b, h) + aoff + m * 2048 + k * 1024); } while (0)
; #define PG8_LDB(dst, b, h) do { _Pragma("unroll") for (int n = 0; n < 2; ++n) _Pragma("unroll") for (int k = 0; k < 2; ++k) dst[n][k] = *(const PG8_LAS bf16x8*)(lds + PG8_SB(b, h) + boff + n * 2048 + k * 1024); } while (0)
; #define PG8_MMA(ai, bj, At, Bt) do { __builtin_amdgcn_s_setprio(1); _Pragma("unroll") for (int m = 0; m < 4; ++m) _Pragma("unroll") for (int n = 0; n < 2; ++n) _Pragma("unroll") for (int k = 0; k < 2; ++k) \
;         acc[ai][bj][m][n] = __builtin_amdgcn_mfma_f32_16x16x32_bf16(Bt[n][k], At[m][k], acc[ai][bj][m][n], 0, 0, 0); __builtin_amdgcn_s_setprio(0); } while (0)
; #define PG8_BAR __builtin_amdgcn_s_barrier()
; template <class Epi, class Sched, bool ALIGN_EPI = false, bool SP2 = false>
; __device__ __forceinline__ void gemm_phase(PG8_LAS unsigned char* lds, const Gemm g, const Sched& S, const Epi& E) {
;     ...
;             if constexpr (SP2) {
;             PG8_LDB(B0, 0, 0); PG8_LDB(B1, 0, 1); PG8_SCHED; PG8_LDA(At, 0, 0); PG8_STAGE(PG8_SA(1, 1), a1 + hstep, voffA);
;             PG8_WAIT_V(8); PG8_WAIT_L(0); PG8_BAR; PG8_MMA(0, 0, At, B0); PG8_MMA(0, 1, At, B1); PG8_BAR; PG8_SCHED;
;             PG8_LDA(At, 0, 1); PG8_STAGE(PG8_SB(0, 0), b2, voffB); PG8_STAGE(PG8_SB(0, 1), b2 + hstep, voffB); PG8_STAGE(PG8_SA(0, 0), a2, voffA);
;             PG8_WAIT_V(8); PG8_WAIT_L(0); PG8_BAR; PG8_MMA(1, 0, At, B0); PG8_MMA(1, 1, At, B1); PG8_BAR; PG8_SCHED;
;             PG8_LDB(B0, 1, 0); PG8_LDB(B1, 1, 1); PG8_SCHED; PG8_LDA(At, 1, 0); PG8_STAGE(PG8_SA(0, 1), a2 + hstep, voffA);
;             PG8_WAIT_V(8); PG8_WAIT_L(0); PG8_BAR; PG8_MMA(0, 0, At, B0); PG8_MMA(0, 1, At, B1); PG8_BAR; PG8_SCHED;
;             PG8_LDA(At, 1, 1); PG8_STAGE(PG8_SB(1, 0), b3, voffB); PG8_STAGE(PG8_SB(1, 1), b3 + hstep, voffB); PG8_STAGE(PG8_SA(1, 0), a3, voffA);
;             PG8_WAIT_V(8); PG8_WAIT_L(0); PG8_BAR; PG8_MMA(1, 0, At, B0); PG8_MMA(1, 1, At, B1); PG8_BAR; PG8_SCHED;
	s_setprio 1
	s_waitcnt lgkmcnt(0)
	v_mfma_f32_16x16x32_bf16 v[62:65], v[156:159], v[220:223], v[62:65]
	v_mfma_f32_16x16x32_bf16 v[62:65], v[160:163], v[224:227], v[62:65]
	v_mfma_f32_16x16x32_bf16 v[58:61], v[196:199], v[220:223], v[58:61]
	v_mfma_f32_16x16x32_bf16 v[58:61], v[200:203], v[224:227], v[58:61]
	v_mfma_f32_16x16x32_bf16 v[46:49], v[156:159], v[228:231], v[46:49]
	v_mfma_f32_16x16x32_bf16 v[46:49], v[160:163], v[232:235], v[46:49]
	v_mfma_f32_16x16x32_bf16 v[42:45], v[196:199], v[228:231], v[42:45]
	v_mfma_f32_16x16x32_bf16 v[42:45], v[200:203], v[232:235], v[42:45]
	v_mfma_f32_16x16x32_bf16 v[30:33], v[156:159], v[236:239], v[30:33]
	v_mfma_f32_16x16x32_bf16 v[30:33], v[160:163], v[240:243], v[30:33]
	v_mfma_f32_16x16x32_bf16 v[26:29], v[196:199], v[236:239], v[26:29]
	v_mfma_f32_16x16x32_bf16 v[26:29], v[200:203], v[240:243], v[26:29]
	v_mfma_f32_16x16x32_bf16 v[14:17], v[156:159], v[244:247], v[14:17]
	v_mfma_f32_16x16x32_bf16 v[14:17], v[160:163], v[248:251], v[14:17]
	v_mfma_f32_16x16x32_bf16 v[10:13], v[196:199], v[244:247], v[10:13]
	v_mfma_f32_16x16x32_bf16 v[10:13], v[200:203], v[248:251], v[10:13]
	s_setprio 0
	s_setprio 1
	v_mfma_f32_16x16x32_bf16 v[54:57], v[204:207], v[220:223], v[54:57]
	v_mfma_f32_16x16x32_bf16 v[54:57], v[208:211], v[224:227], v[54:57]
	v_mfma_f32_16x16x32_bf16 v[50:53], v[212:215], v[220:223], v[50:53]
	v_mfma_f32_16x16x32_bf16 v[50:53], v[216:219], v[224:227], v[50:53]
	v_mfma_f32_16x16x32_bf16 v[38:41], v[204:207], v[228:231], v[38:41]
	v_mfma_f32_16x16x32_bf16 v[38:41], v[208:211], v[232:235], v[38:41]
	v_mfma_f32_16x16x32_bf16 v[34:37], v[212:215], v[228:231], v[34:37]
	v_mfma_f32_16x16x32_bf16 v[34:37], v[216:219], v[232:235], v[34:37]
	v_mfma_f32_16x16x32_bf16 v[22:25], v[204:207], v[236:239], v[22:25]
	v_mfma_f32_16x16x32_bf16 v[22:25], v[208:211], v[240:243], v[22:25]
	v_mfma_f32_16x16x32_bf16 v[18:21], v[212:215], v[236:239], v[18:21]
	v_mfma_f32_16x16x32_bf16 v[18:21], v[216:219], v[240:243], v[18:21]
	v_mfma_f32_16x16x32_bf16 v[6:9], v[204:207], v[244:247], v[6:9]
	v_mfma_f32_16x16x32_bf16 v[6:9], v[208:211], v[248:251], v[6:9]
	v_mfma_f32_16x16x32_bf16 v[2:5], v[212:215], v[244:247], v[2:5]
	v_mfma_f32_16x16x32_bf16 v[2:5], v[216:219], v[248:251], v[2:5]
	s_setprio 0
	s_barrier
	s_add_i32 s62, 0, 0x18000
	v_add_u32_e32 v145, s62, v166
	s_add_i32 s63, 0, 0x1c000
	ds_read_b128 v[156:159], v145
	ds_read_b128 v[160:163], v145 offset:1024
	ds_read_b128 v[196:199], v145 offset:2048
	ds_read_b128 v[200:203], v145 offset:3072
	v_add_u32_e32 v145, s63, v166
	ds_read_b128 v[204:207], v145
	ds_read_b128 v[208:211], v145 offset:1024
	ds_read_b128 v[212:215], v145 offset:2048
	ds_read_b128 v[216:219], v145 offset:3072
	v_lshl_add_u64 v[164:165], s[46:47], 0, v[130:131]
	s_mov_b32 m0, s30
	s_nop 0
	global_load_lds_dwordx4 v[164:165], off
	v_lshl_add_u64 v[164:165], s[46:47], 0, v[134:135]
	s_mov_b32 m0, s31
	s_nop 0
	global_load_lds_dwordx4 v[164:165], off
	s_add_u32 s46, s46, 0x4000
	s_addc_u32 s47, s47, 0
	s_mov_b32 m0, s35
	v_lshl_add_u64 v[164:165], s[46:47], 0, v[130:131]
	ds_read_b128 v[220:223], v186 offset:32768
	ds_read_b128 v[224:227], v186 offset:33792
	ds_read_b128 v[228:231], v186 offset:34816
	ds_read_b128 v[232:235], v186 offset:35840
	ds_read_b128 v[236:239], v186 offset:36864
	ds_read_b128 v[240:243], v186 offset:37888
	ds_read_b128 v[244:247], v186 offset:38912
	ds_read_b128 v[248:251], v186 offset:39936
	global_load_lds_dwordx4 v[164:165], off
	v_lshl_add_u64 v[164:165], s[46:47], 0, v[134:135]
	s_mov_b32 m0, s48
	s_nop 0
	global_load_lds_dwordx4 v[164:165], off
	s_waitcnt vmcnt(8)
	s_waitcnt lgkmcnt(0)
	s_barrier
; #define PG8_STAGE(bufoff, gbase, voff) do { _Pragma("unroll") for (int _i = 0; _i < 2; ++_i) \
;         __builtin_amdgcn_global_load_lds((const unsigned*)((const char*)(gbase) + (voff)[_i]), (PG8_LAS unsigned*)(lds + (bufoff) + ldsw + _i * 8192), 16, 0, 0); } while (0)
; #define PG8_LDA(dst, b, h) do { _Pragma("unroll") for (int m = 0; m < 4; ++m) _Pragma("unroll") for (int k = 0; k < 2; ++k) dst[m][k] = *(const PG8_LAS bf16x8*)(lds + PG8_SA(b, h) + aoff + m * 2048 + k * 1024); } while (0)
; #define PG8_LDB(dst, b, h) do { _Pragma("unroll") for (int n = 0; n < 2; ++n) _Pragma("unroll") for (int k = 0; k < 2; ++k) dst[n][k] = *(const PG8_LAS bf16x8*)(lds + PG8_SB(b, h) + boff + n * 2048 + k * 1024); } while (0)
; #define PG8_MMA(ai, bj, At, Bt) do { __builtin_amdgcn_s_setprio(1); _Pragma("unroll") for (int m = 0; m < 4; ++m) _Pragma("unroll") for (int n = 0; n < 2; ++n) _Pragma("unroll") for (int k = 0; k < 2; ++k) \
;         acc[ai][bj][m][n] = __builtin_amdgcn_mfma_f32_16x16x32_bf16(Bt[n][k], At[m][k], acc[ai][bj][m][n], 0, 0, 0); __builtin_amdgcn_s_setprio(0); } while (0)
; #define PG8_BAR __builtin_amdgcn_s_barrier()
; template <class Epi, class Sched, bool ALIGN_EPI = false, bool SP2 = false>
; __device__ __forceinline__ void gemm_phase(PG8_LAS unsigned char* lds, const Gemm g, const Sched& S, const Epi& E) {
;     ...
;             if constexpr (SP2) {
;             PG8_LDB(B0, 0, 0); PG8_LDB(B1, 0, 1); PG8_SCHED; PG8_LDA(At, 0, 0); PG8_STAGE(PG8_SA(1, 1), a1 + hstep, voffA);
;             PG8_WAIT_V(8); PG8_WAIT_L(0); PG8_BAR; PG8_MMA(0, 0, At, B0); PG8_MMA(0, 1, At, B1); PG8_BAR; PG8_SCHED;
;             PG8_LDA(At, 0, 1); PG8_STAGE(PG8_SB(0, 0), b2, voffB); PG8_STAGE(PG8_SB(0, 1), b2 + hstep, voffB); PG8_STAGE(PG8_SA(0, 0), a2, voffA);
;             PG8_WAIT_V(8); PG8_WAIT_L(0); PG8_BAR; PG8_MMA(1, 0, At, B0); PG8_MMA(1, 1, At, B1); PG8_BAR; PG8_SCHED;
;             PG8_LDB(B0, 1, 0); PG8_LDB(B1, 1, 1); PG8_SCHED; PG8_LDA(At, 1, 0); PG8_STAGE(PG8_SA(0, 1), a2 + hstep, voffA);
;             PG8_WAIT_V(8); PG8_WAIT_L(0); PG8_BAR; PG8_MMA(0, 0, At, B0); PG8_MMA(0, 1, At, B1); PG8_BAR; PG8_SCHED;
;             PG8_LDA(At, 1, 1); PG8_STAGE(PG8_SB(1, 0), b3, voffB); PG8_STAGE(PG8_SB(1, 1), b3 + hstep, voffB); PG8_STAGE(PG8_SA(1, 0), a3, voffA);
;             PG8_WAIT_V(8); PG8_WAIT_L(0); PG8_BAR; PG8_MMA(1, 0, At, B0); PG8_MMA(1, 1, At, B1); PG8_BAR; PG8_SCHED;
	s_setprio 1
	s_waitcnt lgkmcnt(0)
	v_mfma_f32_16x16x32_bf16 v[126:129], v[156:159], v[220:223], v[126:129]
	v_mfma_f32_16x16x32_bf16 v[126:129], v[160:163], v[224:227], v[126:129]
	v_mfma_f32_16x16x32_bf16 v[122:125], v[196:199], v[220:223], v[122:125]
	v_mfma_f32_16x16x32_bf16 v[122:125], v[200:203], v[224:227], v[122:125]
	v_mfma_f32_16x16x32_bf16 v[110:113], v[156:159], v[228:231], v[110:113]
	v_mfma_f32_16x16x32_bf16 v[110:113], v[160:163], v[232:235], v[110:113]
	v_mfma_f32_16x16x32_bf16 v[106:109], v[196:199], v[228:231], v[106:109]
	v_mfma_f32_16x16x32_bf16 v[106:109], v[200:203], v[232:235], v[106:109]
	v_mfma_f32_16x16x32_bf16 v[94:97], v[156:159], v[236:239], v[94:97]
	v_mfma_f32_16x16x32_bf16 v[94:97], v[160:163], v[240:243], v[94:97]
	v_mfma_f32_16x16x32_bf16 v[90:93], v[196:199], v[236:239], v[90:93]
	v_mfma_f32_16x16x32_bf16 v[90:93], v[200:203], v[240:243], v[90:93]
	v_mfma_f32_16x16x32_bf16 v[78:81], v[156:159], v[244:247], v[78:81]
	v_mfma_f32_16x16x32_bf16 v[78:81], v[160:163], v[248:251], v[78:81]
	v_mfma_f32_16x16x32_bf16 v[74:77], v[196:199], v[244:247], v[74:77]
	v_mfma_f32_16x16x32_bf16 v[74:77], v[200:203], v[248:251], v[74:77]
	s_setprio 0
	s_setprio 1
	v_mfma_f32_16x16x32_bf16 v[118:121], v[204:207], v[220:223], v[118:121]
	v_mfma_f32_16x16x32_bf16 v[118:121], v[208:211], v[224:227], v[118:121]
	v_mfma_f32_16x16x32_bf16 v[114:117], v[212:215], v[220:223], v[114:117]
	v_mfma_f32_16x16x32_bf16 v[114:117], v[216:219], v[224:227], v[114:117]
	v_mfma_f32_16x16x32_bf16 v[102:105], v[204:207], v[228:231], v[102:105]
	v_mfma_f32_16x16x32_bf16 v[102:105], v[208:211], v[232:235], v[102:105]
	v_mfma_f32_16x16x32_bf16 v[98:101], v[212:215], v[228:231], v[98:101]
	v_mfma_f32_16x16x32_bf16 v[98:101], v[216:219], v[232:235], v[98:101]
	v_mfma_f32_16x16x32_bf16 v[86:89], v[204:207], v[236:239], v[86:89]
	v_mfma_f32_16x16x32_bf16 v[86:89], v[208:211], v[240:243], v[86:89]
	v_mfma_f32_16x16x32_bf16 v[82:85], v[212:215], v[236:239], v[82:85]
	v_mfma_f32_16x16x32_bf16 v[82:85], v[216:219], v[240:243], v[82:85]
	v_mfma_f32_16x16x32_bf16 v[70:73], v[204:207], v[244:247], v[70:73]
	v_mfma_f32_16x16x32_bf16 v[70:73], v[208:211], v[248:251], v[70:73]
	v_mfma_f32_16x16x32_bf16 v[66:69], v[212:215], v[244:247], v[66:69]
	v_mfma_f32_16x16x32_bf16 v[66:69], v[216:219], v[248:251], v[66:69]
	s_setprio 0
	s_barrier
	s_add_u32 s46, s44, 0x8000
	s_addc_u32 s47, s45, 0
	s_add_i32 s62, s62, s29
	v_lshl_add_u64 v[164:165], s[46:47], 0, v[132:133]
	s_mov_b32 m0, s62
	ds_read_b128 v[220:223], v186 offset:49152
	ds_read_b128 v[224:227], v186 offset:50176
	ds_read_b128 v[228:231], v186 offset:51200
	ds_read_b128 v[232:235], v186 offset:52224
	ds_read_b128 v[236:239], v186 offset:53248
	ds_read_b128 v[240:243], v186 offset:54272
	ds_read_b128 v[244:247], v186 offset:55296
	ds_read_b128 v[248:251], v186 offset:56320
	global_load_lds_dwordx4 v[164:165], off
	s_add_i32 m0, s62, 0x2000
	s_add_u32 s44, s44, 0xc000
	v_lshl_add_u64 v[164:165], s[46:47], 0, v[136:137]
	s_addc_u32 s45, s45, 0
	s_add_i32 s46, s63, s29
	global_load_lds_dwordx4 v[164:165], off
	v_lshl_add_u64 v[164:165], s[44:45], 0, v[132:133]
	s_mov_b32 m0, s46
	s_nop 0
	global_load_lds_dwordx4 v[164:165], off
	v_lshl_add_u64 v[164:165], s[44:45], 0, v[136:137]
	s_add_i32 m0, s46, 0x2000
	s_nop 0
	global_load_lds_dwordx4 v[164:165], off
	s_waitcnt vmcnt(6)
	s_waitcnt lgkmcnt(0)
	s_barrier
	s_setprio 1
	s_waitcnt lgkmcnt(0)
	v_mfma_f32_16x16x32_bf16 v[62:65], v[156:159], v[220:223], v[62:65]
	v_mfma_f32_16x16x32_bf16 v[62:65], v[160:163], v[224:227], v[62:65]
	v_mfma_f32_16x16x32_bf16 v[58:61], v[196:199], v[220:223], v[58:61]
	v_mfma_f32_16x16x32_bf16 v[58:61], v[200:203], v[224:227], v[58:61]
	v_mfma_f32_16x16x32_bf16 v[46:49], v[156:159], v[228:231], v[46:49]
	v_mfma_f32_16x16x32_bf16 v[46:49], v[160:163], v[232:235], v[46:49]
	v_mfma_f32_16x16x32_bf16 v[42:45], v[196:199], v[228:231], v[42:45]
	v_mfma_f32_16x16x32_bf16 v[42:45], v[200:203], v[232:235], v[42:45]
	v_mfma_f32_16x16x32_bf16 v[30:33], v[156:159], v[236:239], v[30:33]
	v_mfma_f32_16x16x32_bf16 v[30:33], v[160:163], v[240:243], v[30:33]
	v_mfma_f32_16x16x32_bf16 v[26:29], v[196:199], v[236:239], v[26:29]
	v_mfma_f32_16x16x32_bf16 v[26:29], v[200:203], v[240:243], v[26:29]
	v_mfma_f32_16x16x32_bf16 v[14:17], v[156:159], v[244:247], v[14:17]
	v_mfma_f32_16x16x32_bf16 v[14:17], v[160:163], v[248:251], v[14:17]
	v_mfma_f32_16x16x32_bf16 v[10:13], v[196:199], v[244:247], v[10:13]
	v_mfma_f32_16x16x32_bf16 v[10:13], v[200:203], v[248:251], v[10:13]
	s_setprio 0
	s_setprio 1
	v_mfma_f32_16x16x32_bf16 v[54:57], v[204:207], v[220:223], v[54:57]
	v_mfma_f32_16x16x32_bf16 v[54:57], v[208:211], v[224:227], v[54:57]
	v_mfma_f32_16x16x32_bf16 v[50:53], v[212:215], v[220:223], v[50:53]
	v_mfma_f32_16x16x32_bf16 v[50:53], v[216:219], v[224:227], v[50:53]
	v_mfma_f32_16x16x32_bf16 v[38:41], v[204:207], v[228:231], v[38:41]
	v_mfma_f32_16x16x32_bf16 v[38:41], v[208:211], v[232:235], v[38:41]
	v_mfma_f32_16x16x32_bf16 v[34:37], v[212:215], v[228:231], v[34:37]
	v_mfma_f32_16x16x32_bf16 v[34:37], v[216:219], v[232:235], v[34:37]
	v_mfma_f32_16x16x32_bf16 v[22:25], v[204:207], v[236:239], v[22:25]
	v_mfma_f32_16x16x32_bf16 v[22:25], v[208:211], v[240:243], v[22:25]
	v_mfma_f32_16x16x32_bf16 v[18:21], v[212:215], v[236:239], v[18:21]
	v_mfma_f32_16x16x32_bf16 v[18:21], v[216:219], v[240:243], v[18:21]
	v_mfma_f32_16x16x32_bf16 v[6:9], v[204:207], v[244:247], v[6:9]
	v_mfma_f32_16x16x32_bf16 v[6:9], v[208:211], v[248:251], v[6:9]
	v_mfma_f32_16x16x32_bf16 v[2:5], v[212:215], v[244:247], v[2:5]
	v_mfma_f32_16x16x32_bf16 v[2:5], v[216:219], v[248:251], v[2:5]
	s_setprio 0
	s_barrier
	s_cmpk_gt_u32 s59, 0xa9
	s_mov_b32 s59, s24
	s_cbranch_scc0 .LBB0_939
	s_and_b64 vcc, exec, s[38:39]
	s_cbranch_vccz .LBB0_942
	s_barrier
